# speedup vs baseline: 1.0043x; 1.0043x over previous
; #define WAIT_V(n) asm volatile("s_waitcnt vmcnt(" #n ")" ::: "memory")
; #define BAR __builtin_amdgcn_s_barrier()
; template <int N, int K, int EPI>
; __device__ void gemm_phase(const u16* __restrict__ A, const u16* __restrict__ Bt, const EpiArgs ea, char* smem, int tid) {
;     ...
;   const int wid = __builtin_amdgcn_readfirstlane(tidl >> 6);
;   const int lane = tidl & 63, wr = wid >> 2, wc = wid & 3, fr = lane & 15, fq = lane >> 4;
;   const int tb = tidl * 16;
;   unsigned off0b;
;   { int R, C; stage_rc((tidl & 63) * 16 + wid * 1024, R, C); off0b = (unsigned)(R * K + C) * 2u; }
;   const unsigned lds0 = (unsigned)(size_t)(__attribute__((address_space(3))) char*)smem;
;   int pm, pn; tile_map(v, nN, pm, pn);
;   const u16* Ab = A + (size_t)pm * BM * K;
;   const u16* Bb = Bt + (size_t)pn * BM * K;
;   f32x4 acc[2][2][4][2] = {};
;   bf16x8 At[4][2], B0[2][2], B1[2][2];
;   STAGE(SB(0, 0), GP(Bb, 0, 0)); STAGE(SA(0, 0), GP(Ab, 0, 0));
;   STAGE(SB(0, 1), GP(Bb, 1, 0)); STAGE(SA(0, 1), GP(Ab, 1, 0));
;   if (wr == 1) BAR;
;   WAIT_V(4); BAR;
;   STAGE(SB(1, 0), GP(Bb, 0, 1)); STAGE(SA(1, 0), GP(Ab, 0, 1)); STAGE(SB(1, 1), GP(Bb, 1, 1));
;   WAIT_V(6); BAR;
.LBB0_60:
	s_and_b32 s20, s2, 3
	s_add_u32 s2, s14, 0x80
	s_addc_u32 s3, s15, 0
	s_add_u32 s4, s14, 0x20080
	s_addc_u32 s5, s15, 0
	s_add_u32 s8, s12, 0x80
	s_addc_u32 s9, s13, 0
	s_add_u32 s10, s12, 0x20080
	s_addc_u32 s11, s13, 0
	s_add_u32 s16, s14, 0x40080
	s_addc_u32 s17, s15, 0
	s_add_u32 s18, s14, 0x60080
	v_readlane_b32 s21, v227, 60
	s_addc_u32 s19, s15, 0
	s_waitcnt vmcnt(2)
	s_barrier
	s_add_i32 s35, s1, s21
	s_mov_b32 m0, s35
	s_nop 0
	global_load_lds_dwordx4 v130, s[2:3]
	v_and_b32_e32 v131, 15, v0
	s_add_i32 s36, s25, 0x1a000
	s_mov_b32 m0, s36
	s_nop 0
	global_load_lds_dwordx4 v130, s[4:5]
	v_lshlrev_b32_e32 v3, 2, v0
	v_lshrrev_b32_e32 v132, 4, v1
	s_add_i32 s37, s25, 0x8000
	s_mov_b32 m0, s37
	s_nop 0
	global_load_lds_dwordx4 v130, s[8:9]
	v_and_b32_e32 v1, 48, v0
	v_lshlrev_b32_e32 v2, 6, v131
	v_and_b32_e32 v3, 32, v3
	s_add_i32 s42, s25, 0xa000
	s_mov_b32 m0, s42
	s_nop 0
	global_load_lds_dwordx4 v130, s[10:11]
	v_readlane_b32 s3, v227, 61
	v_bitop3_b32 v2, v2, v3, v1 bitop3:0x36
	s_add_i32 s2, 0, 0x10000
	s_add_i32 s43, s1, s3
	s_mov_b32 m0, s43
	s_nop 0
	global_load_lds_dwordx4 v130, s[16:17]
	v_add_u32_e32 v4, s2, v2
	s_add_i32 s2, 0, 0x14000
	s_add_i32 s66, s25, 0x1e000
	s_mov_b32 m0, s66
	s_nop 0
	global_load_lds_dwordx4 v130, s[18:19]
	v_add_u32_e32 v5, s2, v2
	v_lshlrev_b32_e32 v0, 6, v0
	s_movk_i32 s2, 0x3c0
	s_waitcnt vmcnt(6)
	s_lshl_b32 s1, s20, 12
	s_lshl_b32 s67, s0, 6
	v_add_u32_e32 v6, s21, v2
	v_add_u32_e32 v7, s3, v2
	s_lshl_b32 s0, s0, 13
	v_add_u32_e32 v2, 0, v2
	v_and_or_b32 v0, v0, s2, v1
	v_xad_u32 v134, v0, v3, 0
	s_or_b32 s89, s0, 0x800
	s_or_b32 s2, s0, 0x1000
	s_or_b32 s3, s0, 0x1800
	v_add_u32_e32 v135, s1, v4
	v_add_u32_e32 v136, s0, v2
	v_add_u32_e32 v139, s1, v5
	v_add_u32_e32 v140, s1, v6
	v_add_u32_e32 v141, s1, v7
	v_readlane_b32 s0, v227, 9
	s_add_i32 s72, s25, 0xc000
	s_add_i32 s73, s25, 0xe000
	s_lshl_b32 s88, s20, 5
	v_add_u32_e32 v137, s2, v134
	v_add_u32_e32 v138, s3, v134
	s_mov_b32 s24, s0
	v_readlane_b32 s95, v227, 8
	v_readlane_b32 s94, v226, 8
	s_barrier
	v_readlane_b32 s1, v227, 10
	v_and_b32_e32 v120, 15, v164
	v_bfe_u32 v121, v164, 4, 2
	v_lshrrev_b32_e32 v122, 3, v120
	v_and_b32_e32 v123, 7, v120
	v_lshlrev_b32_e32 v124, 10, v122
	v_lshl_add_u32 v124, v123, 7, v124
	v_lshl_add_u32 v124, v122, 6, v124
	v_bfe_u32 v125, v120, 1, 2
	v_xor_b32_e32 v125, v125, v121
	v_lshl_add_u32 v124, v125, 4, v124
	v_lshrrev_b32_e32 v126, 8, v164
	v_lshl_add_u32 v136, v126, 13, v124
	v_xor_b32_e32 v137, 64, v136
	v_bfe_u32 v126, v164, 6, 2
	v_lshl_add_u32 v126, v126, 12, v124
	v_add_u32_e32 v135, 0x10000, v126
	v_xor_b32_e32 v139, 64, v135

.LBB0_64:
	ds_read_b128 v[142:145], v135
	ds_read_b128 v[166:169], v139
	ds_read_b128 v[170:173], v135 offset:2048
	ds_read_b128 v[174:177], v139 offset:2048
	s_add_u32 s18, s16, 0x40080
	s_addc_u32 s19, s17, 0
	s_add_u32 s20, s16, 0x60080
	s_addc_u32 s21, s17, 0
	s_cmp_eq_u32 s3, 12
	s_cselect_b32 vcc_lo, s11, s15
	s_cselect_b32 vcc_hi, s10, s14
	s_cselect_b32 s82, s9, s13
	s_cselect_b32 s83, s8, s12
	s_nop 0
	ds_read_b128 v[178:181], v136
	ds_read_b128 v[182:185], v137
	ds_read_b128 v[186:189], v136 offset:2048
	ds_read_b128 v[190:193], v137 offset:2048
	ds_read_b128 v[194:197], v136 offset:4096
	ds_read_b128 v[198:201], v137 offset:4096
	ds_read_b128 v[202:205], v136 offset:6144
	ds_read_b128 v[206:209], v137 offset:6144
	s_mov_b32 m0, s72
	s_nop 0
	global_load_lds_dwordx4 v130, s[18:19]
	s_nop 0
	s_mov_b32 m0, s73
	s_nop 0
	global_load_lds_dwordx4 v130, s[20:21]
	ds_read_b128 v[210:213], v135 offset:16384
	ds_read_b128 v[214:217], v139 offset:16384
	ds_read_b128 v[218:221], v135 offset:18432
	ds_read_b128 v[222:225], v139 offset:18432
	s_waitcnt vmcnt(8) lgkmcnt(0)
	s_barrier
	s_setprio 1
	s_waitcnt lgkmcnt(7)
	v_mfma_f32_16x16x32_bf16 v[124:127], v[142:145], v[178:181], v[124:127]
	v_mfma_f32_16x16x32_bf16 v[120:123], v[170:173], v[178:181], v[120:123]
	s_waitcnt lgkmcnt(5)
	v_mfma_f32_16x16x32_bf16 v[116:119], v[142:145], v[186:189], v[116:119]
	v_mfma_f32_16x16x32_bf16 v[112:115], v[170:173], v[186:189], v[112:115]
	s_waitcnt lgkmcnt(3)
	v_mfma_f32_16x16x32_bf16 v[108:111], v[142:145], v[194:197], v[108:111]
	v_mfma_f32_16x16x32_bf16 v[104:107], v[170:173], v[194:197], v[104:107]
	s_waitcnt lgkmcnt(1)
	v_mfma_f32_16x16x32_bf16 v[100:103], v[142:145], v[202:205], v[100:103]
	v_mfma_f32_16x16x32_bf16 v[96:99], v[170:173], v[202:205], v[96:99]
	v_mfma_f32_16x16x32_bf16 v[124:127], v[166:169], v[182:185], v[124:127]
	v_mfma_f32_16x16x32_bf16 v[120:123], v[174:177], v[182:185], v[120:123]
	v_mfma_f32_16x16x32_bf16 v[116:119], v[166:169], v[190:193], v[116:119]
	v_mfma_f32_16x16x32_bf16 v[112:115], v[174:177], v[190:193], v[112:115]
	v_mfma_f32_16x16x32_bf16 v[108:111], v[166:169], v[198:201], v[108:111]
	v_mfma_f32_16x16x32_bf16 v[104:107], v[174:177], v[198:201], v[104:107]
	s_waitcnt lgkmcnt(0)
	v_mfma_f32_16x16x32_bf16 v[100:103], v[166:169], v[206:209], v[100:103]
	v_mfma_f32_16x16x32_bf16 v[96:99], v[174:177], v[206:209], v[96:99]
	s_setprio 0
	s_setprio 1
	s_waitcnt lgkmcnt(3)
	v_mfma_f32_16x16x32_bf16 v[92:95], v[210:213], v[178:181], v[92:95]
	s_waitcnt lgkmcnt(1)
	v_mfma_f32_16x16x32_bf16 v[88:91], v[218:221], v[178:181], v[88:91]
	v_mfma_f32_16x16x32_bf16 v[84:87], v[210:213], v[186:189], v[84:87]
	v_mfma_f32_16x16x32_bf16 v[80:83], v[218:221], v[186:189], v[80:83]
	v_mfma_f32_16x16x32_bf16 v[76:79], v[210:213], v[194:197], v[76:79]
	v_mfma_f32_16x16x32_bf16 v[72:75], v[218:221], v[194:197], v[72:75]
	v_mfma_f32_16x16x32_bf16 v[68:71], v[210:213], v[202:205], v[68:71]
	v_mfma_f32_16x16x32_bf16 v[64:67], v[218:221], v[202:205], v[64:67]
	v_mfma_f32_16x16x32_bf16 v[92:95], v[214:217], v[182:185], v[92:95]
	s_waitcnt lgkmcnt(0)
	v_mfma_f32_16x16x32_bf16 v[88:91], v[222:225], v[182:185], v[88:91]
	v_mfma_f32_16x16x32_bf16 v[84:87], v[214:217], v[190:193], v[84:87]
	v_mfma_f32_16x16x32_bf16 v[80:83], v[222:225], v[190:193], v[80:83]
	v_mfma_f32_16x16x32_bf16 v[76:79], v[214:217], v[198:201], v[76:79]
	v_mfma_f32_16x16x32_bf16 v[72:75], v[222:225], v[198:201], v[72:75]
	v_mfma_f32_16x16x32_bf16 v[68:71], v[214:217], v[206:209], v[68:71]
	v_mfma_f32_16x16x32_bf16 v[64:67], v[222:225], v[206:209], v[64:67]
	s_setprio 0
	s_barrier
	s_cselect_b32 s70, 0, s5
	s_lshl_b64 s[92:93], s[70:71], 1
	s_add_u32 s18, vcc_hi, s92
	s_addc_u32 s19, vcc_lo, s93
	s_add_u32 s20, s18, 0x20000
	s_mov_b32 m0, s26
	s_nop 0
	global_load_lds_dwordx4 v130, s[18:19]
	s_addc_u32 s21, s19, 0
	s_mov_b32 m0, s27
	s_nop 0
	global_load_lds_dwordx4 v130, s[20:21]
	ds_read_b128 v[178:181], v136 offset:16384
	ds_read_b128 v[182:185], v137 offset:16384
	ds_read_b128 v[186:189], v136 offset:18432
	ds_read_b128 v[190:193], v137 offset:18432
	ds_read_b128 v[194:197], v136 offset:20480
	ds_read_b128 v[198:201], v137 offset:20480
	ds_read_b128 v[202:205], v136 offset:22528
	ds_read_b128 v[206:209], v137 offset:22528
	s_add_u32 s20, s83, s92
	s_addc_u32 s21, s82, s93
	s_add_u32 s82, s20, 0x20000
	s_mov_b32 m0, s25
	s_nop 0
	global_load_lds_dwordx4 v130, s[20:21]
	s_addc_u32 s83, s21, 0
	s_mov_b32 m0, s28
	s_nop 0
	global_load_lds_dwordx4 v130, s[82:83]
	s_add_u32 vcc_hi, vcc_hi, 0x40000
	s_addc_u32 vcc_lo, vcc_lo, 0
	s_add_u32 s82, vcc_hi, s92
	s_addc_u32 s83, vcc_lo, s93
	s_add_u32 s92, s82, 0x20000
	s_mov_b32 m0, s29
	s_nop 0
	global_load_lds_dwordx4 v130, s[82:83]
	s_addc_u32 s93, s83, 0
	s_mov_b32 m0, s30
	s_nop 0
	global_load_lds_dwordx4 v130, s[92:93]
	s_waitcnt vmcnt(8) lgkmcnt(0)
	s_barrier
	s_setprio 1
	s_waitcnt lgkmcnt(7)
	v_mfma_f32_16x16x32_bf16 v[60:63], v[142:145], v[178:181], v[60:63]
	v_mfma_f32_16x16x32_bf16 v[56:59], v[170:173], v[178:181], v[56:59]
	s_waitcnt lgkmcnt(5)
	v_mfma_f32_16x16x32_bf16 v[52:55], v[142:145], v[186:189], v[52:55]
	v_mfma_f32_16x16x32_bf16 v[48:51], v[170:173], v[186:189], v[48:51]
	s_waitcnt lgkmcnt(3)
	v_mfma_f32_16x16x32_bf16 v[44:47], v[142:145], v[194:197], v[44:47]
	v_mfma_f32_16x16x32_bf16 v[40:43], v[170:173], v[194:197], v[40:43]
	s_waitcnt lgkmcnt(1)
	v_mfma_f32_16x16x32_bf16 v[36:39], v[142:145], v[202:205], v[36:39]
	v_mfma_f32_16x16x32_bf16 v[32:35], v[170:173], v[202:205], v[32:35]
	v_mfma_f32_16x16x32_bf16 v[60:63], v[166:169], v[182:185], v[60:63]
	v_mfma_f32_16x16x32_bf16 v[56:59], v[174:177], v[182:185], v[56:59]
	v_mfma_f32_16x16x32_bf16 v[52:55], v[166:169], v[190:193], v[52:55]
	v_mfma_f32_16x16x32_bf16 v[48:51], v[174:177], v[190:193], v[48:51]
	v_mfma_f32_16x16x32_bf16 v[44:47], v[166:169], v[198:201], v[44:47]
	v_mfma_f32_16x16x32_bf16 v[40:43], v[174:177], v[198:201], v[40:43]
	s_waitcnt lgkmcnt(0)
	v_mfma_f32_16x16x32_bf16 v[36:39], v[166:169], v[206:209], v[36:39]
	v_mfma_f32_16x16x32_bf16 v[32:35], v[174:177], v[206:209], v[32:35]
	s_setprio 0
	s_setprio 1
	v_mfma_f32_16x16x32_bf16 v[28:31], v[210:213], v[178:181], v[28:31]
	v_mfma_f32_16x16x32_bf16 v[24:27], v[218:221], v[178:181], v[24:27]
	v_mfma_f32_16x16x32_bf16 v[20:23], v[210:213], v[186:189], v[20:23]
	v_mfma_f32_16x16x32_bf16 v[16:19], v[218:221], v[186:189], v[16:19]
	v_mfma_f32_16x16x32_bf16 v[12:15], v[210:213], v[194:197], v[12:15]
	v_mfma_f32_16x16x32_bf16 v[8:11], v[218:221], v[194:197], v[8:11]
	v_mfma_f32_16x16x32_bf16 v[4:7], v[210:213], v[202:205], v[4:7]
	v_mfma_f32_16x16x32_bf16 v[0:3], v[218:221], v[202:205], v[0:3]
	v_mfma_f32_16x16x32_bf16 v[28:31], v[214:217], v[182:185], v[28:31]
	v_mfma_f32_16x16x32_bf16 v[24:27], v[222:225], v[182:185], v[24:27]
	v_mfma_f32_16x16x32_bf16 v[20:23], v[214:217], v[190:193], v[20:23]
	v_mfma_f32_16x16x32_bf16 v[16:19], v[222:225], v[190:193], v[16:19]
	v_mfma_f32_16x16x32_bf16 v[12:15], v[214:217], v[198:201], v[12:15]
	v_mfma_f32_16x16x32_bf16 v[8:11], v[222:225], v[198:201], v[8:11]
	v_mfma_f32_16x16x32_bf16 v[4:7], v[214:217], v[206:209], v[4:7]
	v_mfma_f32_16x16x32_bf16 v[0:3], v[222:225], v[206:209], v[0:3]
	s_setprio 0
	s_barrier
	ds_read_b128 v[142:145], v135 offset:32768
	ds_read_b128 v[166:169], v139 offset:32768
	ds_read_b128 v[170:173], v135 offset:34816
	ds_read_b128 v[174:177], v139 offset:34816
	ds_read_b128 v[178:181], v136 offset:32768
	ds_read_b128 v[182:185], v137 offset:32768
	ds_read_b128 v[186:189], v136 offset:34816
	ds_read_b128 v[190:193], v137 offset:34816
	ds_read_b128 v[194:197], v136 offset:36864
	ds_read_b128 v[198:201], v137 offset:36864
	ds_read_b128 v[202:205], v136 offset:38912
	ds_read_b128 v[206:209], v137 offset:38912
	s_add_u32 s82, s20, 0x40000
	s_addc_u32 s83, s21, 0
	s_add_u32 s92, s20, 0x60000
	s_mov_b32 m0, s31
	s_nop 0
	global_load_lds_dwordx4 v130, s[82:83]
	s_addc_u32 s93, s21, 0
	s_mov_b32 m0, s34
	s_nop 0
	global_load_lds_dwordx4 v130, s[92:93]
	ds_read_b128 v[210:213], v135 offset:49152
	ds_read_b128 v[214:217], v139 offset:49152
	ds_read_b128 v[218:221], v135 offset:51200
	ds_read_b128 v[222:225], v139 offset:51200
	s_waitcnt vmcnt(8) lgkmcnt(0)
	s_barrier
	s_setprio 1
	s_waitcnt lgkmcnt(7)
	v_mfma_f32_16x16x32_bf16 v[124:127], v[142:145], v[178:181], v[124:127]
	v_mfma_f32_16x16x32_bf16 v[120:123], v[170:173], v[178:181], v[120:123]
	s_waitcnt lgkmcnt(5)
	v_mfma_f32_16x16x32_bf16 v[116:119], v[142:145], v[186:189], v[116:119]
	v_mfma_f32_16x16x32_bf16 v[112:115], v[170:173], v[186:189], v[112:115]
	s_waitcnt lgkmcnt(3)
	v_mfma_f32_16x16x32_bf16 v[108:111], v[142:145], v[194:197], v[108:111]
	v_mfma_f32_16x16x32_bf16 v[104:107], v[170:173], v[194:197], v[104:107]
	s_waitcnt lgkmcnt(1)
	v_mfma_f32_16x16x32_bf16 v[100:103], v[142:145], v[202:205], v[100:103]
	v_mfma_f32_16x16x32_bf16 v[96:99], v[170:173], v[202:205], v[96:99]
	v_mfma_f32_16x16x32_bf16 v[124:127], v[166:169], v[182:185], v[124:127]
	v_mfma_f32_16x16x32_bf16 v[120:123], v[174:177], v[182:185], v[120:123]
	v_mfma_f32_16x16x32_bf16 v[116:119], v[166:169], v[190:193], v[116:119]
	v_mfma_f32_16x16x32_bf16 v[112:115], v[174:177], v[190:193], v[112:115]
	v_mfma_f32_16x16x32_bf16 v[108:111], v[166:169], v[198:201], v[108:111]
	v_mfma_f32_16x16x32_bf16 v[104:107], v[174:177], v[198:201], v[104:107]
	s_waitcnt lgkmcnt(0)
	v_mfma_f32_16x16x32_bf16 v[100:103], v[166:169], v[206:209], v[100:103]
	v_mfma_f32_16x16x32_bf16 v[96:99], v[174:177], v[206:209], v[96:99]
	s_setprio 0
	s_setprio 1
	s_waitcnt lgkmcnt(3)
	v_mfma_f32_16x16x32_bf16 v[92:95], v[210:213], v[178:181], v[92:95]
	s_waitcnt lgkmcnt(1)
	v_mfma_f32_16x16x32_bf16 v[88:91], v[218:221], v[178:181], v[88:91]
	v_mfma_f32_16x16x32_bf16 v[84:87], v[210:213], v[186:189], v[84:87]
	v_mfma_f32_16x16x32_bf16 v[80:83], v[218:221], v[186:189], v[80:83]
	v_mfma_f32_16x16x32_bf16 v[76:79], v[210:213], v[194:197], v[76:79]
	v_mfma_f32_16x16x32_bf16 v[72:75], v[218:221], v[194:197], v[72:75]
	v_mfma_f32_16x16x32_bf16 v[68:71], v[210:213], v[202:205], v[68:71]
	v_mfma_f32_16x16x32_bf16 v[64:67], v[218:221], v[202:205], v[64:67]
	v_mfma_f32_16x16x32_bf16 v[92:95], v[214:217], v[182:185], v[92:95]
	s_waitcnt lgkmcnt(0)
	v_mfma_f32_16x16x32_bf16 v[88:91], v[222:225], v[182:185], v[88:91]
	v_mfma_f32_16x16x32_bf16 v[84:87], v[214:217], v[190:193], v[84:87]
	v_mfma_f32_16x16x32_bf16 v[80:83], v[222:225], v[190:193], v[80:83]
	v_mfma_f32_16x16x32_bf16 v[76:79], v[214:217], v[198:201], v[76:79]
	v_mfma_f32_16x16x32_bf16 v[72:75], v[222:225], v[198:201], v[72:75]
	v_mfma_f32_16x16x32_bf16 v[68:71], v[214:217], v[206:209], v[68:71]
	v_mfma_f32_16x16x32_bf16 v[64:67], v[222:225], v[206:209], v[64:67]
	s_setprio 0
	s_barrier
; template <int N, int K, int EPI>
; __device__ void gemm_phase(const u16* __restrict__ A, const u16* __restrict__ Bt, const EpiArgs ea, char* smem, int tid) {
;     ...
;     for (int t = 0; t < nt; t += 2) {
;       const bool lastit = (t == nt - 2);
;       const u16* A2 = lastit ? Abn : Ab;
;       const u16* B2 = lastit ? Bbn : Bb;
;       const int k2 = lastit ? 0 : t + 2;
;       BODY(Ab, t + 1, A2, B2, k2, k2 + 1);
	s_or_b32 s70, s70, 64
	s_add_u32 s82, s18, 0x80
	s_addc_u32 s83, s19, 0
	s_add_u32 s18, s18, 0x20080
	s_mov_b32 m0, s35
	s_nop 0
	global_load_lds_dwordx4 v130, s[82:83]
	s_addc_u32 s19, s19, 0
	s_mov_b32 m0, s36
	s_nop 0
	global_load_lds_dwordx4 v130, s[18:19]
	ds_read_b128 v[178:181], v136 offset:49152
	ds_read_b128 v[182:185], v137 offset:49152
	ds_read_b128 v[186:189], v136 offset:51200
	ds_read_b128 v[190:193], v137 offset:51200
	ds_read_b128 v[194:197], v136 offset:53248
	ds_read_b128 v[198:201], v137 offset:53248
	ds_read_b128 v[202:205], v136 offset:55296
	ds_read_b128 v[206:209], v137 offset:55296
	s_add_u32 s18, s20, 0x80
	s_addc_u32 s19, s21, 0
	s_add_u32 s20, s20, 0x20080
	s_mov_b32 m0, s37
	s_nop 0
	global_load_lds_dwordx4 v130, s[18:19]
	s_addc_u32 s21, s21, 0
	s_mov_b32 m0, s42
	s_nop 0
	global_load_lds_dwordx4 v130, s[20:21]
	s_lshl_b64 s[18:19], s[70:71], 1
	s_add_u32 s18, vcc_hi, s18
	s_addc_u32 s19, vcc_lo, s19
	s_add_u32 s20, s18, 0x20000
	s_mov_b32 m0, s43
	s_nop 0
	global_load_lds_dwordx4 v130, s[18:19]
	s_addc_u32 s21, s19, 0
	s_mov_b32 m0, s66
	s_nop 0
	global_load_lds_dwordx4 v130, s[20:21]
	s_waitcnt vmcnt(8) lgkmcnt(0)
	s_barrier
	s_setprio 1
	s_waitcnt lgkmcnt(7)
	v_mfma_f32_16x16x32_bf16 v[60:63], v[142:145], v[178:181], v[60:63]
	v_mfma_f32_16x16x32_bf16 v[56:59], v[170:173], v[178:181], v[56:59]
	s_waitcnt lgkmcnt(5)
	v_mfma_f32_16x16x32_bf16 v[52:55], v[142:145], v[186:189], v[52:55]
	v_mfma_f32_16x16x32_bf16 v[48:51], v[170:173], v[186:189], v[48:51]
	s_waitcnt lgkmcnt(3)
	v_mfma_f32_16x16x32_bf16 v[44:47], v[142:145], v[194:197], v[44:47]
	v_mfma_f32_16x16x32_bf16 v[40:43], v[170:173], v[194:197], v[40:43]
	s_waitcnt lgkmcnt(1)
	v_mfma_f32_16x16x32_bf16 v[36:39], v[142:145], v[202:205], v[36:39]
	v_mfma_f32_16x16x32_bf16 v[32:35], v[170:173], v[202:205], v[32:35]
	v_mfma_f32_16x16x32_bf16 v[60:63], v[166:169], v[182:185], v[60:63]
	v_mfma_f32_16x16x32_bf16 v[56:59], v[174:177], v[182:185], v[56:59]
	v_mfma_f32_16x16x32_bf16 v[52:55], v[166:169], v[190:193], v[52:55]
	v_mfma_f32_16x16x32_bf16 v[48:51], v[174:177], v[190:193], v[48:51]
	v_mfma_f32_16x16x32_bf16 v[44:47], v[166:169], v[198:201], v[44:47]
	v_mfma_f32_16x16x32_bf16 v[40:43], v[174:177], v[198:201], v[40:43]
	s_waitcnt lgkmcnt(0)
	v_mfma_f32_16x16x32_bf16 v[36:39], v[166:169], v[206:209], v[36:39]
	v_mfma_f32_16x16x32_bf16 v[32:35], v[174:177], v[206:209], v[32:35]
	s_setprio 0
	s_setprio 1
	v_mfma_f32_16x16x32_bf16 v[28:31], v[210:213], v[178:181], v[28:31]
	v_mfma_f32_16x16x32_bf16 v[24:27], v[218:221], v[178:181], v[24:27]
	v_mfma_f32_16x16x32_bf16 v[20:23], v[210:213], v[186:189], v[20:23]
	v_mfma_f32_16x16x32_bf16 v[16:19], v[218:221], v[186:189], v[16:19]
	v_mfma_f32_16x16x32_bf16 v[12:15], v[210:213], v[194:197], v[12:15]
	v_mfma_f32_16x16x32_bf16 v[8:11], v[218:221], v[194:197], v[8:11]
	v_mfma_f32_16x16x32_bf16 v[4:7], v[210:213], v[202:205], v[4:7]
	v_mfma_f32_16x16x32_bf16 v[0:3], v[218:221], v[202:205], v[0:3]
	v_mfma_f32_16x16x32_bf16 v[28:31], v[214:217], v[182:185], v[28:31]
	v_mfma_f32_16x16x32_bf16 v[24:27], v[222:225], v[182:185], v[24:27]
	v_mfma_f32_16x16x32_bf16 v[20:23], v[214:217], v[190:193], v[20:23]
	v_mfma_f32_16x16x32_bf16 v[16:19], v[222:225], v[190:193], v[16:19]
	v_mfma_f32_16x16x32_bf16 v[12:15], v[214:217], v[198:201], v[12:15]
	v_mfma_f32_16x16x32_bf16 v[8:11], v[222:225], v[198:201], v[8:11]
	v_mfma_f32_16x16x32_bf16 v[4:7], v[214:217], v[206:209], v[4:7]
	v_mfma_f32_16x16x32_bf16 v[0:3], v[222:225], v[206:209], v[0:3]
	s_setprio 0
	s_add_i32 s3, s3, 2
	s_addk_i32 s5, 0x80
	s_add_u32 s16, s16, 0x100
	s_addc_u32 s17, s17, 0
	s_cmp_gt_u32 s3, 13
	s_barrier
	s_cbranch_scc0 .LBB0_64
; #define WAIT_V(n) asm volatile("s_waitcnt vmcnt(" #n ")" ::: "memory")
; #define BAR __builtin_amdgcn_s_barrier()
; template <int N, int K, int EPI>
; __device__ void gemm_phase(const u16* __restrict__ A, const u16* __restrict__ Bt, const EpiArgs ea, char* smem, int tid) {
;     ...
;         u16* f = ea.o0;
; #pragma unroll
;         for (int ai = 0; ai < 2; ++ai)
; #pragma unroll
;           for (int bj = 0; bj < 2; ++bj)
; #pragma unroll
;             for (int m = 0; m < 4; ++m) {
;               const int row = brow + ai * HALF + wr * 64 + m * 16 + fr_e;
;               const int col = pn * BM + bj * HALF + wc * 32 + fq_e * 8;
;               const f32x4 v0 = acc[ai][bj][m][0], v1 = acc[ai][bj][m][1];
;               u32x4 o = {pk_bf16(v0[0], v0[1]), pk_bf16(v0[2], v0[3]), pk_bf16(v1[0], v1[1]), pk_bf16(v1[2], v1[3])};
;               *(u32x4*)(f + (size_t)row * N + col) = o;
;             }
;     ...
;   WAIT_V(0);
;   if (wr == 0) BAR;
	s_lshl_b32 s3, s24, 8
	v_mov_b32_e32 v128, v131
	v_mov_b32_e32 v129, v132
	s_add_i32 s3, s3, s67
	v_cvt_pk_bf16_f32 v124, v124, v125
	v_cvt_pk_bf16_f32 v125, v126, v127
	v_cvt_pk_bf16_f32 v126, v120, v121
	v_cvt_pk_bf16_f32 v127, v122, v123
	v_cvt_pk_bf16_f32 v116, v116, v117
	s_nop 0
	v_add_u32_e32 v142, s3, v128
	s_lshl_b32 s3, s95, 8
	s_or_b32 s3, s3, s88
	v_lshl_add_u32 v144, v129, 3, s3
	v_ashrrev_i32_e32 v145, 31, v144
	v_ashrrev_i32_e32 v143, 31, v142
	v_lshl_add_u64 v[128:129], v[144:145], 1, s[64:65]
	v_lshlrev_b64 v[120:121], 11, v[142:143]
	v_lshl_add_u64 v[122:123], v[128:129], 0, v[120:121]
	global_store_dwordx4 v[122:123], v[124:127], off
	v_add_u32_e32 v122, 16, v142
	v_ashrrev_i32_e32 v123, 31, v122
	v_cvt_pk_bf16_f32 v117, v118, v119
	v_cvt_pk_bf16_f32 v118, v112, v113
	v_lshlrev_b64 v[112:113], 11, v[122:123]
	v_cvt_pk_bf16_f32 v119, v114, v115
	v_lshl_add_u64 v[114:115], v[128:129], 0, v[112:113]
	global_store_dwordx4 v[114:115], v[116:119], off
	v_add_u32_e32 v114, 32, v142
	v_ashrrev_i32_e32 v115, 31, v114
	v_cvt_pk_bf16_f32 v108, v108, v109
	v_cvt_pk_bf16_f32 v109, v110, v111
	v_cvt_pk_bf16_f32 v110, v104, v105
	v_lshlrev_b64 v[104:105], 11, v[114:115]
	v_cvt_pk_bf16_f32 v111, v106, v107
	v_lshl_add_u64 v[106:107], v[128:129], 0, v[104:105]
	global_store_dwordx4 v[106:107], v[108:111], off
	v_add_u32_e32 v106, 48, v142
	v_ashrrev_i32_e32 v107, 31, v106
	v_cvt_pk_bf16_f32 v100, v100, v101
	v_cvt_pk_bf16_f32 v101, v102, v103
	v_cvt_pk_bf16_f32 v102, v96, v97
	v_lshlrev_b64 v[96:97], 11, v[106:107]
	v_cvt_pk_bf16_f32 v103, v98, v99
	v_lshl_add_u64 v[98:99], v[128:129], 0, v[96:97]
	global_store_dwordx4 v[98:99], v[100:103], off
	v_add_u32_e32 v98, 0x80, v144
	v_ashrrev_i32_e32 v99, 31, v98
	v_lshl_add_u64 v[98:99], v[98:99], 1, s[64:65]
	v_cvt_pk_bf16_f32 v68, v68, v69
	v_cvt_pk_bf16_f32 v69, v70, v71
	v_cvt_pk_bf16_f32 v70, v64, v65
	v_lshl_add_u64 v[64:65], v[98:99], 0, v[96:97]
	v_cvt_pk_bf16_f32 v71, v66, v67
	global_store_dwordx4 v[64:65], v[68:71], off
	v_add_u32_e32 v64, 0x80, v142
	v_ashrrev_i32_e32 v65, 31, v64
	v_cvt_pk_bf16_f32 v60, v60, v61
	v_cvt_pk_bf16_f32 v61, v62, v63
	v_cvt_pk_bf16_f32 v62, v56, v57
	v_lshlrev_b64 v[56:57], 11, v[64:65]
	v_cvt_pk_bf16_f32 v92, v92, v93
	v_cvt_pk_bf16_f32 v93, v94, v95
	v_cvt_pk_bf16_f32 v94, v88, v89
	v_lshl_add_u64 v[88:89], v[98:99], 0, v[120:121]
	v_cvt_pk_bf16_f32 v84, v84, v85
	v_cvt_pk_bf16_f32 v85, v86, v87
	v_cvt_pk_bf16_f32 v86, v80, v81
	v_lshl_add_u64 v[80:81], v[98:99], 0, v[112:113]
	v_cvt_pk_bf16_f32 v76, v76, v77
	v_cvt_pk_bf16_f32 v77, v78, v79
	v_cvt_pk_bf16_f32 v78, v72, v73
	v_lshl_add_u64 v[72:73], v[98:99], 0, v[104:105]
	v_cvt_pk_bf16_f32 v63, v58, v59
	v_lshl_add_u64 v[58:59], v[128:129], 0, v[56:57]
	v_cvt_pk_bf16_f32 v95, v90, v91
	global_store_dwordx4 v[88:89], v[92:95], off
	v_cvt_pk_bf16_f32 v87, v82, v83
	global_store_dwordx4 v[80:81], v[84:87], off
	v_cvt_pk_bf16_f32 v79, v74, v75
	global_store_dwordx4 v[72:73], v[76:79], off
	global_store_dwordx4 v[58:59], v[60:63], off
	v_add_u32_e32 v58, 0x90, v142
	v_ashrrev_i32_e32 v59, 31, v58
	v_cvt_pk_bf16_f32 v52, v52, v53
	v_cvt_pk_bf16_f32 v53, v54, v55
	v_cvt_pk_bf16_f32 v54, v48, v49
	v_lshlrev_b64 v[48:49], 11, v[58:59]
	v_cvt_pk_bf16_f32 v55, v50, v51
	v_lshl_add_u64 v[50:51], v[128:129], 0, v[48:49]
	global_store_dwordx4 v[50:51], v[52:55], off
	v_add_u32_e32 v50, 0xa0, v142
	v_ashrrev_i32_e32 v51, 31, v50
	v_cvt_pk_bf16_f32 v44, v44, v45
	v_cvt_pk_bf16_f32 v45, v46, v47
	v_cvt_pk_bf16_f32 v46, v40, v41
	v_lshlrev_b64 v[40:41], 11, v[50:51]
	v_cvt_pk_bf16_f32 v47, v42, v43
	v_lshl_add_u64 v[42:43], v[128:129], 0, v[40:41]
	global_store_dwordx4 v[42:43], v[44:47], off
	v_add_u32_e32 v42, 0xb0, v142
	v_ashrrev_i32_e32 v43, 31, v42
	v_cvt_pk_bf16_f32 v36, v36, v37
	v_cvt_pk_bf16_f32 v37, v38, v39
	v_cvt_pk_bf16_f32 v38, v32, v33
	v_lshlrev_b64 v[32:33], 11, v[42:43]
	v_cvt_pk_bf16_f32 v39, v34, v35
	v_lshl_add_u64 v[34:35], v[128:129], 0, v[32:33]
	v_cvt_pk_bf16_f32 v28, v28, v29
	v_cvt_pk_bf16_f32 v29, v30, v31
	v_cvt_pk_bf16_f32 v30, v24, v25
	v_lshl_add_u64 v[24:25], v[98:99], 0, v[56:57]
	v_cvt_pk_bf16_f32 v20, v20, v21
	v_cvt_pk_bf16_f32 v21, v22, v23
	v_cvt_pk_bf16_f32 v22, v16, v17
	v_lshl_add_u64 v[16:17], v[98:99], 0, v[48:49]
	v_cvt_pk_bf16_f32 v12, v12, v13
	v_cvt_pk_bf16_f32 v13, v14, v15
	v_cvt_pk_bf16_f32 v14, v8, v9
	v_lshl_add_u64 v[8:9], v[98:99], 0, v[40:41]
	v_cvt_pk_bf16_f32 v4, v4, v5
	v_cvt_pk_bf16_f32 v5, v6, v7
	v_cvt_pk_bf16_f32 v6, v0, v1
	v_lshl_add_u64 v[0:1], v[98:99], 0, v[32:33]
	s_and_b64 vcc, exec, s[0:1]
	s_mov_b32 s24, s2
	s_mov_b32 s95, s4
	s_mov_b64 s[14:15], s[10:11]
	s_mov_b64 s[12:13], s[8:9]
	global_store_dwordx4 v[34:35], v[36:39], off
	v_cvt_pk_bf16_f32 v31, v26, v27
	global_store_dwordx4 v[24:25], v[28:31], off
	v_cvt_pk_bf16_f32 v23, v18, v19
	global_store_dwordx4 v[16:17], v[20:23], off
	v_cvt_pk_bf16_f32 v15, v10, v11
	global_store_dwordx4 v[8:9], v[12:15], off
	v_cvt_pk_bf16_f32 v7, v2, v3
	global_store_dwordx4 v[0:1], v[4:7], off
	s_cbranch_vccz .LBB0_61
	s_waitcnt vmcnt(0)
	v_readlane_b32 s0, v226, 16
	v_readlane_b32 s36, v226, 30
	v_readlane_b32 s18, v226, 22
	v_readlane_b32 s92, v226, 20
	s_cmpk_gt_u32 s0, 0xff
	v_readlane_b32 s37, v226, 31
	v_readlane_b32 s31, v226, 34
	v_readlane_b32 s42, v226, 29
	v_readlane_b32 s43, v226, 28
	v_readlane_b32 s66, v226, 27
	v_readlane_b32 s67, v226, 26
	v_readlane_b32 s19, v226, 23
	v_readlane_b32 s93, v226, 21
	s_cbranch_scc1 .LBB0_68
	s_barrier

; #define WAIT_V(n) asm volatile("s_waitcnt vmcnt(" #n ")" ::: "memory")
; #define BAR __builtin_amdgcn_s_barrier()
; template <int N, int K, int EPI>
; __device__ void gemm_phase(const u16* __restrict__ A, const u16* __restrict__ Bt, const EpiArgs ea, char* smem, int tid) {
;     ...
;   const int wid = __builtin_amdgcn_readfirstlane(tidl >> 6);
;   const int lane = tidl & 63, wr = wid >> 2, wc = wid & 3, fr = lane & 15, fq = lane >> 4;
;   const int tb = tidl * 16;
;   unsigned off0b;
;   { int R, C; stage_rc((tidl & 63) * 16 + wid * 1024, R, C); off0b = (unsigned)(R * K + C) * 2u; }
;   const unsigned lds0 = (unsigned)(size_t)(__attribute__((address_space(3))) char*)smem;
;   int pm, pn; tile_map(v, nN, pm, pn);
;   const u16* Ab = A + (size_t)pm * BM * K;
;   const u16* Bb = Bt + (size_t)pn * BM * K;
;   f32x4 acc[2][2][4][2] = {};
;   bf16x8 At[4][2], B0[2][2], B1[2][2];
;   STAGE(SB(0, 0), GP(Bb, 0, 0)); STAGE(SA(0, 0), GP(Ab, 0, 0));
;   STAGE(SB(0, 1), GP(Bb, 1, 0)); STAGE(SA(0, 1), GP(Ab, 1, 0));
;   if (wr == 1) BAR;
;   WAIT_V(4); BAR;
;   STAGE(SB(1, 0), GP(Bb, 0, 1)); STAGE(SA(1, 0), GP(Ab, 0, 1)); STAGE(SB(1, 1), GP(Bb, 1, 1));
;   WAIT_V(6); BAR;
.LBB0_105:
	s_and_b32 s18, s2, 3
	s_add_u32 s2, s12, 0x80
	s_addc_u32 s3, s13, 0
	s_add_u32 s6, s12, 0x20080
	s_addc_u32 s7, s13, 0
	s_add_u32 s8, s4, 0x80
	s_addc_u32 s9, s5, 0
	s_add_u32 s10, s4, 0x20080
	s_addc_u32 s11, s5, 0
	s_add_u32 s14, s12, 0x40080
	s_addc_u32 s15, s13, 0
	s_add_u32 s16, s12, 0x60080
	v_readlane_b32 s19, v227, 60
	v_and_b32_e32 v166, 15, v0
	s_addc_u32 s17, s13, 0
	s_waitcnt vmcnt(2)
	s_barrier
	s_add_i32 s31, s1, s19
	s_mov_b32 m0, s31
	s_nop 0
	global_load_lds_dwordx4 v165, s[2:3]
	v_lshlrev_b32_e32 v3, 2, v0
	v_lshrrev_b32_e32 v167, 4, v1
	s_add_i32 s34, s23, 0x1a000
	s_mov_b32 m0, s34
	s_nop 0
	global_load_lds_dwordx4 v165, s[6:7]
	v_and_b32_e32 v1, 48, v0
	v_lshlrev_b32_e32 v2, 6, v166
	v_and_b32_e32 v3, 32, v3
	s_add_i32 s35, s23, 0x8000
	s_mov_b32 m0, s35
	s_nop 0
	global_load_lds_dwordx4 v165, s[8:9]
	v_bitop3_b32 v2, v2, v3, v1 bitop3:0x36
	s_add_i32 s2, 0, 0x10000
	s_add_i32 s36, s23, 0xa000
	s_mov_b32 m0, s36
	s_nop 0
	global_load_lds_dwordx4 v165, s[10:11]
	v_readlane_b32 s3, v227, 61
	v_add_u32_e32 v4, s2, v2
	s_add_i32 s2, 0, 0x14000
	s_lshl_b32 s22, s18, 5
	s_add_i32 s37, s1, s3
	s_mov_b32 m0, s37
	s_nop 0
	global_load_lds_dwordx4 v165, s[14:15]
	v_add_u32_e32 v5, s2, v2
	s_or_b32 s2, s22, 0xfffffc00
	s_add_i32 s42, s23, 0x1e000
	s_mov_b32 m0, s42
	s_nop 0
	global_load_lds_dwordx4 v165, s[16:17]
	v_writelane_b32 v226, s2, 38
	v_lshlrev_b32_e32 v0, 6, v0
	s_movk_i32 s2, 0x3c0
	s_waitcnt vmcnt(6)
	s_lshl_b32 s1, s18, 12
	s_lshl_b32 s43, s0, 6
	v_add_u32_e32 v6, s19, v2
	v_add_u32_e32 v7, s3, v2
	s_lshl_b32 s0, s0, 13
	v_add_u32_e32 v2, 0, v2
	v_and_or_b32 v0, v0, s2, v1
	v_xad_u32 v168, v0, v3, 0
	s_or_b32 s94, s0, 0x800
	s_or_b32 s2, s0, 0x1000
	s_or_b32 s3, s0, 0x1800
	v_add_u32_e32 v169, s1, v4
	v_add_u32_e32 v170, s0, v2
	v_add_u32_e32 v173, s1, v5
	v_add_u32_e32 v174, s1, v6
	v_add_u32_e32 v175, s1, v7
	v_readlane_b32 s0, v227, 22
	s_add_i32 s66, s23, 0xc000
	s_add_i32 s67, s23, 0xe000
	v_add_u32_e32 v171, s2, v168
	v_add_u32_e32 v172, s3, v168
	s_mov_b32 s97, s0
	v_readlane_b32 s96, v227, 21
	s_barrier
	v_readlane_b32 s1, v227, 23
	v_and_b32_e32 v120, 15, v164
	v_bfe_u32 v121, v164, 4, 2
	v_lshrrev_b32_e32 v122, 3, v120
	v_and_b32_e32 v123, 7, v120
	v_lshlrev_b32_e32 v124, 10, v122
	v_lshl_add_u32 v124, v123, 7, v124
	v_lshl_add_u32 v124, v122, 6, v124
	v_bfe_u32 v125, v120, 1, 2
	v_xor_b32_e32 v125, v125, v121
	v_lshl_add_u32 v124, v125, 4, v124
	v_lshrrev_b32_e32 v126, 8, v164
	v_lshl_add_u32 v170, v126, 13, v124
	v_xor_b32_e32 v171, 64, v170
	v_bfe_u32 v126, v164, 6, 2
	v_lshl_add_u32 v126, v126, 12, v124
	v_add_u32_e32 v169, 0x10000, v126
	v_xor_b32_e32 v173, 64, v169
	s_branch .LBB0_107

.LBB0_110:
	ds_read_b128 v[128:131], v169
	ds_read_b128 v[134:137], v173
	ds_read_b128 v[138:141], v169 offset:2048
	ds_read_b128 v[142:145], v173 offset:2048
	s_add_u32 s16, s14, 0x40080
	s_addc_u32 s17, s15, 0
	s_add_u32 s18, s14, 0x60080
	s_addc_u32 s19, s15, 0
	s_cmp_eq_u32 s3, 12
	s_cselect_b32 s82, s11, s13
	s_cselect_b32 s83, s10, s12
	s_cselect_b32 s88, s9, s5
	s_cselect_b32 s89, s8, s4
	s_nop 0
	ds_read_b128 v[176:179], v170
	ds_read_b128 v[180:183], v171
	ds_read_b128 v[184:187], v170 offset:2048
	ds_read_b128 v[188:191], v171 offset:2048
	ds_read_b128 v[192:195], v170 offset:4096
	ds_read_b128 v[196:199], v171 offset:4096
	ds_read_b128 v[200:203], v170 offset:6144
	ds_read_b128 v[204:207], v171 offset:6144
	s_mov_b32 m0, s66
	s_nop 0
	global_load_lds_dwordx4 v165, s[16:17]
	s_nop 0
	s_mov_b32 m0, s67
	s_nop 0
	global_load_lds_dwordx4 v165, s[18:19]
	ds_read_b128 v[208:211], v169 offset:16384
	ds_read_b128 v[212:215], v173 offset:16384
	ds_read_b128 v[216:219], v169 offset:18432
	ds_read_b128 v[220:223], v173 offset:18432
	s_waitcnt vmcnt(8) lgkmcnt(0)
	s_barrier
	s_setprio 1
	s_waitcnt lgkmcnt(7)
	v_mfma_f32_16x16x32_bf16 v[124:127], v[128:131], v[176:179], v[124:127]
	v_mfma_f32_16x16x32_bf16 v[120:123], v[138:141], v[176:179], v[120:123]
	s_waitcnt lgkmcnt(5)
	v_mfma_f32_16x16x32_bf16 v[116:119], v[128:131], v[184:187], v[116:119]
	v_mfma_f32_16x16x32_bf16 v[112:115], v[138:141], v[184:187], v[112:115]
	s_waitcnt lgkmcnt(3)
	v_mfma_f32_16x16x32_bf16 v[108:111], v[128:131], v[192:195], v[108:111]
	v_mfma_f32_16x16x32_bf16 v[104:107], v[138:141], v[192:195], v[104:107]
	s_waitcnt lgkmcnt(1)
	v_mfma_f32_16x16x32_bf16 v[100:103], v[128:131], v[200:203], v[100:103]
	v_mfma_f32_16x16x32_bf16 v[96:99], v[138:141], v[200:203], v[96:99]
	v_mfma_f32_16x16x32_bf16 v[124:127], v[134:137], v[180:183], v[124:127]
	v_mfma_f32_16x16x32_bf16 v[120:123], v[142:145], v[180:183], v[120:123]
	v_mfma_f32_16x16x32_bf16 v[116:119], v[134:137], v[188:191], v[116:119]
	v_mfma_f32_16x16x32_bf16 v[112:115], v[142:145], v[188:191], v[112:115]
	v_mfma_f32_16x16x32_bf16 v[108:111], v[134:137], v[196:199], v[108:111]
	v_mfma_f32_16x16x32_bf16 v[104:107], v[142:145], v[196:199], v[104:107]
	s_waitcnt lgkmcnt(0)
	v_mfma_f32_16x16x32_bf16 v[100:103], v[134:137], v[204:207], v[100:103]
	v_mfma_f32_16x16x32_bf16 v[96:99], v[142:145], v[204:207], v[96:99]
	s_setprio 0
	s_setprio 1
	s_waitcnt lgkmcnt(3)
	v_mfma_f32_16x16x32_bf16 v[92:95], v[208:211], v[176:179], v[92:95]
	s_waitcnt lgkmcnt(1)
	v_mfma_f32_16x16x32_bf16 v[88:91], v[216:219], v[176:179], v[88:91]
	v_mfma_f32_16x16x32_bf16 v[84:87], v[208:211], v[184:187], v[84:87]
	v_mfma_f32_16x16x32_bf16 v[80:83], v[216:219], v[184:187], v[80:83]
	v_mfma_f32_16x16x32_bf16 v[76:79], v[208:211], v[192:195], v[76:79]
	v_mfma_f32_16x16x32_bf16 v[72:75], v[216:219], v[192:195], v[72:75]
	v_mfma_f32_16x16x32_bf16 v[68:71], v[208:211], v[200:203], v[68:71]
	v_mfma_f32_16x16x32_bf16 v[64:67], v[216:219], v[200:203], v[64:67]
	v_mfma_f32_16x16x32_bf16 v[92:95], v[212:215], v[180:183], v[92:95]
	s_waitcnt lgkmcnt(0)
	v_mfma_f32_16x16x32_bf16 v[88:91], v[220:223], v[180:183], v[88:91]
	v_mfma_f32_16x16x32_bf16 v[84:87], v[212:215], v[188:191], v[84:87]
	v_mfma_f32_16x16x32_bf16 v[80:83], v[220:223], v[188:191], v[80:83]
	v_mfma_f32_16x16x32_bf16 v[76:79], v[212:215], v[196:199], v[76:79]
	v_mfma_f32_16x16x32_bf16 v[72:75], v[220:223], v[196:199], v[72:75]
	v_mfma_f32_16x16x32_bf16 v[68:71], v[212:215], v[204:207], v[68:71]
	v_mfma_f32_16x16x32_bf16 v[64:67], v[220:223], v[204:207], v[64:67]
	s_setprio 0
	s_barrier
	s_cselect_b32 s70, 0, s7
	s_lshl_b64 s[92:93], s[70:71], 1
	s_add_u32 s16, s83, s92
	s_addc_u32 s17, s82, s93
	s_add_u32 s18, s16, 0x20000
	s_mov_b32 m0, s24
	s_nop 0
	global_load_lds_dwordx4 v165, s[16:17]
	s_addc_u32 s19, s17, 0
	s_mov_b32 m0, s25
	s_nop 0
	global_load_lds_dwordx4 v165, s[18:19]
	ds_read_b128 v[176:179], v170 offset:16384
	ds_read_b128 v[180:183], v171 offset:16384
	ds_read_b128 v[184:187], v170 offset:18432
	ds_read_b128 v[188:191], v171 offset:18432
	ds_read_b128 v[192:195], v170 offset:20480
	ds_read_b128 v[196:199], v171 offset:20480
	ds_read_b128 v[200:203], v170 offset:22528
	ds_read_b128 v[204:207], v171 offset:22528
	s_add_u32 s18, s89, s92
	s_addc_u32 s19, s88, s93
	s_add_u32 s88, s18, 0x20000
	s_mov_b32 m0, s23
	s_nop 0
	global_load_lds_dwordx4 v165, s[18:19]
	s_addc_u32 s89, s19, 0
	s_mov_b32 m0, s26
	s_nop 0
	global_load_lds_dwordx4 v165, s[88:89]
	s_add_u32 s83, s83, 0x40000
	s_addc_u32 s82, s82, 0
	s_add_u32 s88, s83, s92
	s_addc_u32 s89, s82, s93
	s_add_u32 s92, s88, 0x20000
	s_mov_b32 m0, s27
	s_nop 0
	global_load_lds_dwordx4 v165, s[88:89]
	s_addc_u32 s93, s89, 0
	s_mov_b32 m0, s28
	s_nop 0
	global_load_lds_dwordx4 v165, s[92:93]
	s_waitcnt vmcnt(8) lgkmcnt(0)
	s_barrier
	s_setprio 1
	s_waitcnt lgkmcnt(7)
	v_mfma_f32_16x16x32_bf16 v[60:63], v[128:131], v[176:179], v[60:63]
	v_mfma_f32_16x16x32_bf16 v[56:59], v[138:141], v[176:179], v[56:59]
	s_waitcnt lgkmcnt(5)
	v_mfma_f32_16x16x32_bf16 v[52:55], v[128:131], v[184:187], v[52:55]
	v_mfma_f32_16x16x32_bf16 v[48:51], v[138:141], v[184:187], v[48:51]
	s_waitcnt lgkmcnt(3)
	v_mfma_f32_16x16x32_bf16 v[44:47], v[128:131], v[192:195], v[44:47]
	v_mfma_f32_16x16x32_bf16 v[40:43], v[138:141], v[192:195], v[40:43]
	s_waitcnt lgkmcnt(1)
	v_mfma_f32_16x16x32_bf16 v[36:39], v[128:131], v[200:203], v[36:39]
	v_mfma_f32_16x16x32_bf16 v[32:35], v[138:141], v[200:203], v[32:35]
	v_mfma_f32_16x16x32_bf16 v[60:63], v[134:137], v[180:183], v[60:63]
	v_mfma_f32_16x16x32_bf16 v[56:59], v[142:145], v[180:183], v[56:59]
	v_mfma_f32_16x16x32_bf16 v[52:55], v[134:137], v[188:191], v[52:55]
	v_mfma_f32_16x16x32_bf16 v[48:51], v[142:145], v[188:191], v[48:51]
	v_mfma_f32_16x16x32_bf16 v[44:47], v[134:137], v[196:199], v[44:47]
	v_mfma_f32_16x16x32_bf16 v[40:43], v[142:145], v[196:199], v[40:43]
	s_waitcnt lgkmcnt(0)
	v_mfma_f32_16x16x32_bf16 v[36:39], v[134:137], v[204:207], v[36:39]
	v_mfma_f32_16x16x32_bf16 v[32:35], v[142:145], v[204:207], v[32:35]
	s_setprio 0
	s_setprio 1
	v_mfma_f32_16x16x32_bf16 v[28:31], v[208:211], v[176:179], v[28:31]
	v_mfma_f32_16x16x32_bf16 v[24:27], v[216:219], v[176:179], v[24:27]
	v_mfma_f32_16x16x32_bf16 v[20:23], v[208:211], v[184:187], v[20:23]
	v_mfma_f32_16x16x32_bf16 v[16:19], v[216:219], v[184:187], v[16:19]
	v_mfma_f32_16x16x32_bf16 v[12:15], v[208:211], v[192:195], v[12:15]
	v_mfma_f32_16x16x32_bf16 v[8:11], v[216:219], v[192:195], v[8:11]
	v_mfma_f32_16x16x32_bf16 v[4:7], v[208:211], v[200:203], v[4:7]
	v_mfma_f32_16x16x32_bf16 v[0:3], v[216:219], v[200:203], v[0:3]
	v_mfma_f32_16x16x32_bf16 v[28:31], v[212:215], v[180:183], v[28:31]
	v_mfma_f32_16x16x32_bf16 v[24:27], v[220:223], v[180:183], v[24:27]
	v_mfma_f32_16x16x32_bf16 v[20:23], v[212:215], v[188:191], v[20:23]
	v_mfma_f32_16x16x32_bf16 v[16:19], v[220:223], v[188:191], v[16:19]
	v_mfma_f32_16x16x32_bf16 v[12:15], v[212:215], v[196:199], v[12:15]
	v_mfma_f32_16x16x32_bf16 v[8:11], v[220:223], v[196:199], v[8:11]
	v_mfma_f32_16x16x32_bf16 v[4:7], v[212:215], v[204:207], v[4:7]
	v_mfma_f32_16x16x32_bf16 v[0:3], v[220:223], v[204:207], v[0:3]
	s_setprio 0
	s_barrier
	ds_read_b128 v[128:131], v169 offset:32768
	ds_read_b128 v[134:137], v173 offset:32768
	ds_read_b128 v[138:141], v169 offset:34816
	ds_read_b128 v[142:145], v173 offset:34816
	ds_read_b128 v[176:179], v170 offset:32768
	ds_read_b128 v[180:183], v171 offset:32768
	ds_read_b128 v[184:187], v170 offset:34816
	ds_read_b128 v[188:191], v171 offset:34816
	ds_read_b128 v[192:195], v170 offset:36864
	ds_read_b128 v[196:199], v171 offset:36864
	ds_read_b128 v[200:203], v170 offset:38912
	ds_read_b128 v[204:207], v171 offset:38912
	s_add_u32 s88, s18, 0x40000
	s_addc_u32 s89, s19, 0
	s_add_u32 s92, s18, 0x60000
	s_mov_b32 m0, s29
	s_nop 0
	global_load_lds_dwordx4 v165, s[88:89]
	s_addc_u32 s93, s19, 0
	s_mov_b32 m0, s30
	s_nop 0
	global_load_lds_dwordx4 v165, s[92:93]
	ds_read_b128 v[208:211], v169 offset:49152
	ds_read_b128 v[212:215], v173 offset:49152
	ds_read_b128 v[216:219], v169 offset:51200
	ds_read_b128 v[220:223], v173 offset:51200
	s_waitcnt vmcnt(8) lgkmcnt(0)
	s_barrier
	s_setprio 1
	s_waitcnt lgkmcnt(7)
	v_mfma_f32_16x16x32_bf16 v[124:127], v[128:131], v[176:179], v[124:127]
	v_mfma_f32_16x16x32_bf16 v[120:123], v[138:141], v[176:179], v[120:123]
	s_waitcnt lgkmcnt(5)
	v_mfma_f32_16x16x32_bf16 v[116:119], v[128:131], v[184:187], v[116:119]
	v_mfma_f32_16x16x32_bf16 v[112:115], v[138:141], v[184:187], v[112:115]
	s_waitcnt lgkmcnt(3)
	v_mfma_f32_16x16x32_bf16 v[108:111], v[128:131], v[192:195], v[108:111]
	v_mfma_f32_16x16x32_bf16 v[104:107], v[138:141], v[192:195], v[104:107]
	s_waitcnt lgkmcnt(1)
	v_mfma_f32_16x16x32_bf16 v[100:103], v[128:131], v[200:203], v[100:103]
	v_mfma_f32_16x16x32_bf16 v[96:99], v[138:141], v[200:203], v[96:99]
	v_mfma_f32_16x16x32_bf16 v[124:127], v[134:137], v[180:183], v[124:127]
	v_mfma_f32_16x16x32_bf16 v[120:123], v[142:145], v[180:183], v[120:123]
	v_mfma_f32_16x16x32_bf16 v[116:119], v[134:137], v[188:191], v[116:119]
	v_mfma_f32_16x16x32_bf16 v[112:115], v[142:145], v[188:191], v[112:115]
	v_mfma_f32_16x16x32_bf16 v[108:111], v[134:137], v[196:199], v[108:111]
	v_mfma_f32_16x16x32_bf16 v[104:107], v[142:145], v[196:199], v[104:107]
	s_waitcnt lgkmcnt(0)
	v_mfma_f32_16x16x32_bf16 v[100:103], v[134:137], v[204:207], v[100:103]
	v_mfma_f32_16x16x32_bf16 v[96:99], v[142:145], v[204:207], v[96:99]
	s_setprio 0
	s_setprio 1
	s_waitcnt lgkmcnt(3)
	v_mfma_f32_16x16x32_bf16 v[92:95], v[208:211], v[176:179], v[92:95]
	s_waitcnt lgkmcnt(1)
	v_mfma_f32_16x16x32_bf16 v[88:91], v[216:219], v[176:179], v[88:91]
	v_mfma_f32_16x16x32_bf16 v[84:87], v[208:211], v[184:187], v[84:87]
	v_mfma_f32_16x16x32_bf16 v[80:83], v[216:219], v[184:187], v[80:83]
	v_mfma_f32_16x16x32_bf16 v[76:79], v[208:211], v[192:195], v[76:79]
	v_mfma_f32_16x16x32_bf16 v[72:75], v[216:219], v[192:195], v[72:75]
	v_mfma_f32_16x16x32_bf16 v[68:71], v[208:211], v[200:203], v[68:71]
	v_mfma_f32_16x16x32_bf16 v[64:67], v[216:219], v[200:203], v[64:67]
	v_mfma_f32_16x16x32_bf16 v[92:95], v[212:215], v[180:183], v[92:95]
	s_waitcnt lgkmcnt(0)
	v_mfma_f32_16x16x32_bf16 v[88:91], v[220:223], v[180:183], v[88:91]
	v_mfma_f32_16x16x32_bf16 v[84:87], v[212:215], v[188:191], v[84:87]
	v_mfma_f32_16x16x32_bf16 v[80:83], v[220:223], v[188:191], v[80:83]
	v_mfma_f32_16x16x32_bf16 v[76:79], v[212:215], v[196:199], v[76:79]
	v_mfma_f32_16x16x32_bf16 v[72:75], v[220:223], v[196:199], v[72:75]
	v_mfma_f32_16x16x32_bf16 v[68:71], v[212:215], v[204:207], v[68:71]
	v_mfma_f32_16x16x32_bf16 v[64:67], v[220:223], v[204:207], v[64:67]
	s_setprio 0
	s_barrier
; template <int N, int K, int EPI>
; __device__ void gemm_phase(const u16* __restrict__ A, const u16* __restrict__ Bt, const EpiArgs ea, char* smem, int tid) {
;     ...
;         if (pn == 4 || pn == 5) {
;           u16* vt = ea.o2;
	s_or_b32 s70, s70, 64
	s_add_u32 s88, s16, 0x80
	s_addc_u32 s89, s17, 0
	s_add_u32 s16, s16, 0x20080
	s_mov_b32 m0, s31
	s_nop 0
	global_load_lds_dwordx4 v165, s[88:89]
	s_addc_u32 s17, s17, 0
	s_mov_b32 m0, s34
	s_nop 0
	global_load_lds_dwordx4 v165, s[16:17]
	ds_read_b128 v[176:179], v170 offset:49152
	ds_read_b128 v[180:183], v171 offset:49152
	ds_read_b128 v[184:187], v170 offset:51200
	ds_read_b128 v[188:191], v171 offset:51200
	ds_read_b128 v[192:195], v170 offset:53248
	ds_read_b128 v[196:199], v171 offset:53248
	ds_read_b128 v[200:203], v170 offset:55296
	ds_read_b128 v[204:207], v171 offset:55296
	s_add_u32 s16, s18, 0x80
	s_addc_u32 s17, s19, 0
	s_add_u32 s18, s18, 0x20080
	s_mov_b32 m0, s35
	s_nop 0
	global_load_lds_dwordx4 v165, s[16:17]
	s_addc_u32 s19, s19, 0
	s_mov_b32 m0, s36
	s_nop 0
	global_load_lds_dwordx4 v165, s[18:19]
	s_lshl_b64 s[16:17], s[70:71], 1
	s_add_u32 s16, s83, s16
	s_addc_u32 s17, s82, s17
	s_add_u32 s18, s16, 0x20000
	s_mov_b32 m0, s37
	s_nop 0
	global_load_lds_dwordx4 v165, s[16:17]
	s_addc_u32 s19, s17, 0
	s_mov_b32 m0, s42
	s_nop 0
	global_load_lds_dwordx4 v165, s[18:19]
	s_waitcnt vmcnt(8) lgkmcnt(0)
	s_barrier
	s_setprio 1
	s_waitcnt lgkmcnt(7)
	v_mfma_f32_16x16x32_bf16 v[60:63], v[128:131], v[176:179], v[60:63]
	v_mfma_f32_16x16x32_bf16 v[56:59], v[138:141], v[176:179], v[56:59]
	s_waitcnt lgkmcnt(5)
	v_mfma_f32_16x16x32_bf16 v[52:55], v[128:131], v[184:187], v[52:55]
	v_mfma_f32_16x16x32_bf16 v[48:51], v[138:141], v[184:187], v[48:51]
	s_waitcnt lgkmcnt(3)
	v_mfma_f32_16x16x32_bf16 v[44:47], v[128:131], v[192:195], v[44:47]
	v_mfma_f32_16x16x32_bf16 v[40:43], v[138:141], v[192:195], v[40:43]
	s_waitcnt lgkmcnt(1)
	v_mfma_f32_16x16x32_bf16 v[36:39], v[128:131], v[200:203], v[36:39]
	v_mfma_f32_16x16x32_bf16 v[32:35], v[138:141], v[200:203], v[32:35]
	v_mfma_f32_16x16x32_bf16 v[60:63], v[134:137], v[180:183], v[60:63]
	v_mfma_f32_16x16x32_bf16 v[56:59], v[142:145], v[180:183], v[56:59]
	v_mfma_f32_16x16x32_bf16 v[52:55], v[134:137], v[188:191], v[52:55]
	v_mfma_f32_16x16x32_bf16 v[48:51], v[142:145], v[188:191], v[48:51]
	v_mfma_f32_16x16x32_bf16 v[44:47], v[134:137], v[196:199], v[44:47]
	v_mfma_f32_16x16x32_bf16 v[40:43], v[142:145], v[196:199], v[40:43]
	s_waitcnt lgkmcnt(0)
	v_mfma_f32_16x16x32_bf16 v[36:39], v[134:137], v[204:207], v[36:39]
	v_mfma_f32_16x16x32_bf16 v[32:35], v[142:145], v[204:207], v[32:35]
	s_setprio 0
	s_setprio 1
	v_mfma_f32_16x16x32_bf16 v[28:31], v[208:211], v[176:179], v[28:31]
	v_mfma_f32_16x16x32_bf16 v[24:27], v[216:219], v[176:179], v[24:27]
	v_mfma_f32_16x16x32_bf16 v[20:23], v[208:211], v[184:187], v[20:23]
	v_mfma_f32_16x16x32_bf16 v[16:19], v[216:219], v[184:187], v[16:19]
	v_mfma_f32_16x16x32_bf16 v[12:15], v[208:211], v[192:195], v[12:15]
	v_mfma_f32_16x16x32_bf16 v[8:11], v[216:219], v[192:195], v[8:11]
	v_mfma_f32_16x16x32_bf16 v[4:7], v[208:211], v[200:203], v[4:7]
	v_mfma_f32_16x16x32_bf16 v[0:3], v[216:219], v[200:203], v[0:3]
	v_mfma_f32_16x16x32_bf16 v[28:31], v[212:215], v[180:183], v[28:31]
	v_mfma_f32_16x16x32_bf16 v[24:27], v[220:223], v[180:183], v[24:27]
	v_mfma_f32_16x16x32_bf16 v[20:23], v[212:215], v[188:191], v[20:23]
	v_mfma_f32_16x16x32_bf16 v[16:19], v[220:223], v[188:191], v[16:19]
	v_mfma_f32_16x16x32_bf16 v[12:15], v[212:215], v[196:199], v[12:15]
	v_mfma_f32_16x16x32_bf16 v[8:11], v[220:223], v[196:199], v[8:11]
	v_mfma_f32_16x16x32_bf16 v[4:7], v[212:215], v[204:207], v[4:7]
	v_mfma_f32_16x16x32_bf16 v[0:3], v[220:223], v[204:207], v[0:3]
	s_setprio 0
	s_add_i32 s3, s3, 2
	s_addk_i32 s7, 0x80
	s_add_u32 s14, s14, 0x100
	s_addc_u32 s15, s15, 0
	s_cmp_gt_u32 s3, 13
	s_barrier
	s_cbranch_scc0 .LBB0_110
	s_lshl_b32 s3, s97, 8
	s_and_b32 s4, s96, -2
	v_mov_b32_e32 v176, v167
	v_mov_b32_e32 v132, v166
	s_cmp_lg_u32 s4, 4
	s_mov_b64 s[4:5], -1
	s_mov_b32 s19, 0x3ffc0
	s_cbranch_scc0 .LBB0_184
	s_cmp_gt_i32 s96, 1
	s_mov_b64 s[14:15], -1
	s_cbranch_scc0 .LBB0_117
	s_lshl_b32 s7, s96, 8
	s_cmp_gt_u32 s96, 3
	s_mov_b64 s[4:5], -1
	s_cbranch_scc0 .LBB0_115
	s_add_i32 s18, s7, 0xfffffa00
	s_mov_b64 s[4:5], 0

; #define WAIT_V(n) asm volatile("s_waitcnt vmcnt(" #n ")" ::: "memory")
; #define BAR __builtin_amdgcn_s_barrier()
; template <int N, int K, int EPI>
; __device__ void gemm_phase(const u16* __restrict__ A, const u16* __restrict__ Bt, const EpiArgs ea, char* smem, int tid) {
;     ...
;   const int wid = __builtin_amdgcn_readfirstlane(tidl >> 6);
;   const int lane = tidl & 63, wr = wid >> 2, wc = wid & 3, fr = lane & 15, fq = lane >> 4;
;   const int tb = tidl * 16;
;   unsigned off0b;
;   { int R, C; stage_rc((tidl & 63) * 16 + wid * 1024, R, C); off0b = (unsigned)(R * K + C) * 2u; }
;   const unsigned lds0 = (unsigned)(size_t)(__attribute__((address_space(3))) char*)smem;
;   int pm, pn; tile_map(v, nN, pm, pn);
;   const u16* Ab = A + (size_t)pm * BM * K;
;   const u16* Bb = Bt + (size_t)pn * BM * K;
;   f32x4 acc[2][2][4][2] = {};
;   bf16x8 At[4][2], B0[2][2], B1[2][2];
;   STAGE(SB(0, 0), GP(Bb, 0, 0)); STAGE(SA(0, 0), GP(Ab, 0, 0));
;   STAGE(SB(0, 1), GP(Bb, 1, 0)); STAGE(SA(0, 1), GP(Ab, 1, 0));
;   if (wr == 1) BAR;
;   WAIT_V(4); BAR;
;   STAGE(SB(1, 0), GP(Bb, 0, 1)); STAGE(SA(1, 0), GP(Ab, 0, 1)); STAGE(SB(1, 1), GP(Bb, 1, 1));
;   WAIT_V(6); BAR;
.LBB0_216:
	s_and_b32 s42, s2, 3
	s_add_u32 s2, s8, 0x80
	s_addc_u32 s3, s9, 0
	s_add_u32 s4, s8, 0x58080
	s_addc_u32 s5, s9, 0
	s_add_u32 s10, s6, 0x80
	s_addc_u32 s11, s7, 0
	s_add_u32 s12, s6, 0x58080
	s_addc_u32 s13, s7, 0
	s_add_u32 s14, s8, 0xb0080
	s_addc_u32 s15, s9, 0
	s_add_u32 s36, s8, 0x108080
	v_readlane_b32 s43, v227, 60
	s_addc_u32 s37, s9, 0
	s_waitcnt vmcnt(2)
	s_barrier
	s_add_i32 s27, s1, s43
	s_mov_b32 m0, s27
	s_nop 0
	global_load_lds_dwordx4 v130, s[2:3]
	v_and_b32_e32 v131, 15, v0
	s_add_i32 s28, s19, 0x1a000
	s_mov_b32 m0, s28
	s_nop 0
	global_load_lds_dwordx4 v130, s[4:5]
	v_lshlrev_b32_e32 v3, 2, v0
	v_lshrrev_b32_e32 v132, 4, v1
	s_add_i32 s29, s19, 0x8000
	s_mov_b32 m0, s29
	s_nop 0
	global_load_lds_dwordx4 v130, s[10:11]
	v_and_b32_e32 v1, 48, v0
	v_lshlrev_b32_e32 v2, 6, v131
	v_and_b32_e32 v3, 32, v3
	s_add_i32 s30, s19, 0xa000
	s_mov_b32 m0, s30
	s_nop 0
	global_load_lds_dwordx4 v130, s[12:13]
	v_readlane_b32 s3, v227, 61
	v_bitop3_b32 v2, v2, v3, v1 bitop3:0x36
	s_add_i32 s2, 0, 0x10000
	s_add_i32 s31, s1, s3
	s_mov_b32 m0, s31
	s_nop 0
	global_load_lds_dwordx4 v130, s[14:15]
	v_add_u32_e32 v4, s2, v2
	s_add_i32 s2, 0, 0x14000
	s_add_i32 s34, s19, 0x1e000
	s_mov_b32 m0, s34
	s_nop 0
	global_load_lds_dwordx4 v130, s[36:37]
	v_add_u32_e32 v5, s2, v2
	v_lshlrev_b32_e32 v0, 6, v0
	s_movk_i32 s2, 0x3c0
	s_waitcnt vmcnt(6)
	s_lshl_b32 s1, s42, 12
	s_lshl_b32 s35, s0, 6
	v_add_u32_e32 v6, s43, v2
	v_add_u32_e32 v7, s3, v2
	s_lshl_b32 s0, s0, 13
	v_add_u32_e32 v2, 0, v2
	v_and_or_b32 v0, v0, s2, v1
	v_xad_u32 v134, v0, v3, 0
	s_or_b32 s43, s0, 0x800
	s_or_b32 s2, s0, 0x1000
	s_or_b32 s3, s0, 0x1800
	v_add_u32_e32 v135, s1, v4
	v_add_u32_e32 v136, s0, v2
	v_add_u32_e32 v139, s1, v5
	v_add_u32_e32 v140, s1, v6
	v_add_u32_e32 v141, s1, v7
	v_readlane_b32 s0, v227, 9
	v_readlane_b32 s73, v227, 8
	s_add_i32 s36, s19, 0xc000
	s_add_i32 s37, s19, 0xe000
	s_lshl_b32 s42, s42, 5
	v_add_u32_e32 v137, s2, v134
	v_add_u32_e32 v138, s3, v134
	s_mov_b32 s88, s0
	s_mov_b32 s95, s94
	s_mov_b32 s66, s94
	s_mov_b32 s67, s0
	s_mov_b32 s72, s73
	s_barrier
	v_readlane_b32 s1, v227, 10
	v_and_b32_e32 v120, 15, v164
	v_bfe_u32 v121, v164, 4, 2
	v_lshrrev_b32_e32 v122, 3, v120
	v_and_b32_e32 v123, 7, v120
	v_lshlrev_b32_e32 v124, 10, v122
	v_lshl_add_u32 v124, v123, 7, v124
	v_lshl_add_u32 v124, v122, 6, v124
	v_bfe_u32 v125, v120, 1, 2
	v_xor_b32_e32 v125, v125, v121
	v_lshl_add_u32 v124, v125, 4, v124
	v_lshrrev_b32_e32 v126, 8, v164
	v_lshl_add_u32 v136, v126, 13, v124
	v_xor_b32_e32 v137, 64, v136
	v_bfe_u32 v126, v164, 6, 2
	v_lshl_add_u32 v126, v126, 12, v124
	v_add_u32_e32 v135, 0x10000, v126
	v_xor_b32_e32 v139, 64, v135

.LBB0_220:
	ds_read_b128 v[142:145], v135
	ds_read_b128 v[166:169], v139
	ds_read_b128 v[170:173], v135 offset:2048
	ds_read_b128 v[174:177], v139 offset:2048
	s_add_u32 s12, s10, 0xb0080
	s_addc_u32 s13, s11, 0
	s_add_u32 s14, s10, 0x108080
	s_addc_u32 s15, s11, 0
	s_cmp_eq_u32 s89, 40
	s_cselect_b32 s82, s5, s9
	s_cselect_b32 s83, s4, s8
	s_cselect_b32 s92, s3, s7
	s_cselect_b32 s93, s2, s6
	s_nop 0
	ds_read_b128 v[178:181], v136
	ds_read_b128 v[182:185], v137
	ds_read_b128 v[186:189], v136 offset:2048
	ds_read_b128 v[190:193], v137 offset:2048
	ds_read_b128 v[194:197], v136 offset:4096
	ds_read_b128 v[198:201], v137 offset:4096
	ds_read_b128 v[202:205], v136 offset:6144
	ds_read_b128 v[206:209], v137 offset:6144
	s_mov_b32 m0, s36
	s_nop 0
	global_load_lds_dwordx4 v130, s[12:13]
	s_nop 0
	s_mov_b32 m0, s37
	s_nop 0
	global_load_lds_dwordx4 v130, s[14:15]
	ds_read_b128 v[210:213], v135 offset:16384
	ds_read_b128 v[214:217], v139 offset:16384
	ds_read_b128 v[218:221], v135 offset:18432
	ds_read_b128 v[222:225], v139 offset:18432
	s_waitcnt vmcnt(8) lgkmcnt(0)
	s_barrier
	s_setprio 1
	s_waitcnt lgkmcnt(7)
	v_mfma_f32_16x16x32_bf16 v[124:127], v[142:145], v[178:181], v[124:127]
	v_mfma_f32_16x16x32_bf16 v[120:123], v[170:173], v[178:181], v[120:123]
	s_waitcnt lgkmcnt(5)
	v_mfma_f32_16x16x32_bf16 v[116:119], v[142:145], v[186:189], v[116:119]
	v_mfma_f32_16x16x32_bf16 v[112:115], v[170:173], v[186:189], v[112:115]
	s_waitcnt lgkmcnt(3)
	v_mfma_f32_16x16x32_bf16 v[108:111], v[142:145], v[194:197], v[108:111]
	v_mfma_f32_16x16x32_bf16 v[104:107], v[170:173], v[194:197], v[104:107]
	s_waitcnt lgkmcnt(1)
	v_mfma_f32_16x16x32_bf16 v[100:103], v[142:145], v[202:205], v[100:103]
	v_mfma_f32_16x16x32_bf16 v[96:99], v[170:173], v[202:205], v[96:99]
	v_mfma_f32_16x16x32_bf16 v[124:127], v[166:169], v[182:185], v[124:127]
	v_mfma_f32_16x16x32_bf16 v[120:123], v[174:177], v[182:185], v[120:123]
	v_mfma_f32_16x16x32_bf16 v[116:119], v[166:169], v[190:193], v[116:119]
	v_mfma_f32_16x16x32_bf16 v[112:115], v[174:177], v[190:193], v[112:115]
	v_mfma_f32_16x16x32_bf16 v[108:111], v[166:169], v[198:201], v[108:111]
	v_mfma_f32_16x16x32_bf16 v[104:107], v[174:177], v[198:201], v[104:107]
	s_waitcnt lgkmcnt(0)
	v_mfma_f32_16x16x32_bf16 v[100:103], v[166:169], v[206:209], v[100:103]
	v_mfma_f32_16x16x32_bf16 v[96:99], v[174:177], v[206:209], v[96:99]
	s_setprio 0
	s_setprio 1
	s_waitcnt lgkmcnt(3)
	v_mfma_f32_16x16x32_bf16 v[92:95], v[210:213], v[178:181], v[92:95]
	s_waitcnt lgkmcnt(1)
	v_mfma_f32_16x16x32_bf16 v[88:91], v[218:221], v[178:181], v[88:91]
	v_mfma_f32_16x16x32_bf16 v[84:87], v[210:213], v[186:189], v[84:87]
	v_mfma_f32_16x16x32_bf16 v[80:83], v[218:221], v[186:189], v[80:83]
	v_mfma_f32_16x16x32_bf16 v[76:79], v[210:213], v[194:197], v[76:79]
	v_mfma_f32_16x16x32_bf16 v[72:75], v[218:221], v[194:197], v[72:75]
	v_mfma_f32_16x16x32_bf16 v[68:71], v[210:213], v[202:205], v[68:71]
	v_mfma_f32_16x16x32_bf16 v[64:67], v[218:221], v[202:205], v[64:67]
	v_mfma_f32_16x16x32_bf16 v[92:95], v[214:217], v[182:185], v[92:95]
	s_waitcnt lgkmcnt(0)
	v_mfma_f32_16x16x32_bf16 v[88:91], v[222:225], v[182:185], v[88:91]
	v_mfma_f32_16x16x32_bf16 v[84:87], v[214:217], v[190:193], v[84:87]
	v_mfma_f32_16x16x32_bf16 v[80:83], v[222:225], v[190:193], v[80:83]
	v_mfma_f32_16x16x32_bf16 v[76:79], v[214:217], v[198:201], v[76:79]
	v_mfma_f32_16x16x32_bf16 v[72:75], v[222:225], v[198:201], v[72:75]
	v_mfma_f32_16x16x32_bf16 v[68:71], v[214:217], v[206:209], v[68:71]
	v_mfma_f32_16x16x32_bf16 v[64:67], v[222:225], v[206:209], v[64:67]
	s_setprio 0
	s_barrier
	s_cselect_b32 s70, 0, s94
	s_lshl_b64 s[96:97], s[70:71], 1
	s_add_u32 s12, s83, s96
	s_addc_u32 s13, s82, s97
	s_add_u32 s14, s12, 0x58000
	s_mov_b32 m0, s20
	s_nop 0
	global_load_lds_dwordx4 v130, s[12:13]
	s_addc_u32 s15, s13, 0
	s_mov_b32 m0, s21
	s_nop 0
	global_load_lds_dwordx4 v130, s[14:15]
	ds_read_b128 v[178:181], v136 offset:16384
	ds_read_b128 v[182:185], v137 offset:16384
	ds_read_b128 v[186:189], v136 offset:18432
	ds_read_b128 v[190:193], v137 offset:18432
	ds_read_b128 v[194:197], v136 offset:20480
	ds_read_b128 v[198:201], v137 offset:20480
	ds_read_b128 v[202:205], v136 offset:22528
	ds_read_b128 v[206:209], v137 offset:22528
	s_add_u32 s14, s93, s96
	s_addc_u32 s15, s92, s97
	s_add_u32 s92, s14, 0x58000
	s_mov_b32 m0, s19
	s_nop 0
	global_load_lds_dwordx4 v130, s[14:15]
	s_addc_u32 s93, s15, 0
	s_mov_b32 m0, s22
	s_nop 0
	global_load_lds_dwordx4 v130, s[92:93]
	s_add_u32 s83, s83, 0xb0000
	s_addc_u32 s82, s82, 0
	s_add_u32 s92, s83, s96
	s_addc_u32 s93, s82, s97
	s_add_u32 s96, s92, 0x58000
	s_mov_b32 m0, s23
	s_nop 0
	global_load_lds_dwordx4 v130, s[92:93]
	s_addc_u32 s97, s93, 0
	s_mov_b32 m0, s24
	s_nop 0
	global_load_lds_dwordx4 v130, s[96:97]
	s_waitcnt vmcnt(8) lgkmcnt(0)
	s_barrier
	s_setprio 1
	s_waitcnt lgkmcnt(7)
	v_mfma_f32_16x16x32_bf16 v[60:63], v[142:145], v[178:181], v[60:63]
	v_mfma_f32_16x16x32_bf16 v[56:59], v[170:173], v[178:181], v[56:59]
	s_waitcnt lgkmcnt(5)
	v_mfma_f32_16x16x32_bf16 v[52:55], v[142:145], v[186:189], v[52:55]
	v_mfma_f32_16x16x32_bf16 v[48:51], v[170:173], v[186:189], v[48:51]
	s_waitcnt lgkmcnt(3)
	v_mfma_f32_16x16x32_bf16 v[44:47], v[142:145], v[194:197], v[44:47]
	v_mfma_f32_16x16x32_bf16 v[40:43], v[170:173], v[194:197], v[40:43]
	s_waitcnt lgkmcnt(1)
	v_mfma_f32_16x16x32_bf16 v[36:39], v[142:145], v[202:205], v[36:39]
	v_mfma_f32_16x16x32_bf16 v[32:35], v[170:173], v[202:205], v[32:35]
	v_mfma_f32_16x16x32_bf16 v[60:63], v[166:169], v[182:185], v[60:63]
	v_mfma_f32_16x16x32_bf16 v[56:59], v[174:177], v[182:185], v[56:59]
	v_mfma_f32_16x16x32_bf16 v[52:55], v[166:169], v[190:193], v[52:55]
	v_mfma_f32_16x16x32_bf16 v[48:51], v[174:177], v[190:193], v[48:51]
	v_mfma_f32_16x16x32_bf16 v[44:47], v[166:169], v[198:201], v[44:47]
	v_mfma_f32_16x16x32_bf16 v[40:43], v[174:177], v[198:201], v[40:43]
	s_waitcnt lgkmcnt(0)
	v_mfma_f32_16x16x32_bf16 v[36:39], v[166:169], v[206:209], v[36:39]
	v_mfma_f32_16x16x32_bf16 v[32:35], v[174:177], v[206:209], v[32:35]
	s_setprio 0
	s_setprio 1
	v_mfma_f32_16x16x32_bf16 v[28:31], v[210:213], v[178:181], v[28:31]
	v_mfma_f32_16x16x32_bf16 v[24:27], v[218:221], v[178:181], v[24:27]
	v_mfma_f32_16x16x32_bf16 v[20:23], v[210:213], v[186:189], v[20:23]
	v_mfma_f32_16x16x32_bf16 v[16:19], v[218:221], v[186:189], v[16:19]
	v_mfma_f32_16x16x32_bf16 v[12:15], v[210:213], v[194:197], v[12:15]
	v_mfma_f32_16x16x32_bf16 v[8:11], v[218:221], v[194:197], v[8:11]
	v_mfma_f32_16x16x32_bf16 v[4:7], v[210:213], v[202:205], v[4:7]
	v_mfma_f32_16x16x32_bf16 v[0:3], v[218:221], v[202:205], v[0:3]
	v_mfma_f32_16x16x32_bf16 v[28:31], v[214:217], v[182:185], v[28:31]
	v_mfma_f32_16x16x32_bf16 v[24:27], v[222:225], v[182:185], v[24:27]
	v_mfma_f32_16x16x32_bf16 v[20:23], v[214:217], v[190:193], v[20:23]
	v_mfma_f32_16x16x32_bf16 v[16:19], v[222:225], v[190:193], v[16:19]
	v_mfma_f32_16x16x32_bf16 v[12:15], v[214:217], v[198:201], v[12:15]
	v_mfma_f32_16x16x32_bf16 v[8:11], v[222:225], v[198:201], v[8:11]
	v_mfma_f32_16x16x32_bf16 v[4:7], v[214:217], v[206:209], v[4:7]
	v_mfma_f32_16x16x32_bf16 v[0:3], v[222:225], v[206:209], v[0:3]
	s_setprio 0
	s_barrier
	ds_read_b128 v[142:145], v135 offset:32768
	ds_read_b128 v[166:169], v139 offset:32768
	ds_read_b128 v[170:173], v135 offset:34816
	ds_read_b128 v[174:177], v139 offset:34816
	ds_read_b128 v[178:181], v136 offset:32768
	ds_read_b128 v[182:185], v137 offset:32768
	ds_read_b128 v[186:189], v136 offset:34816
	ds_read_b128 v[190:193], v137 offset:34816
	ds_read_b128 v[194:197], v136 offset:36864
	ds_read_b128 v[198:201], v137 offset:36864
	ds_read_b128 v[202:205], v136 offset:38912
	ds_read_b128 v[206:209], v137 offset:38912
	s_add_u32 s92, s14, 0xb0000
	s_addc_u32 s93, s15, 0
	s_add_u32 s96, s14, 0x108000
	s_mov_b32 m0, s25
	s_nop 0
	global_load_lds_dwordx4 v130, s[92:93]
	s_addc_u32 s97, s15, 0
	s_mov_b32 m0, s26
	s_nop 0
	global_load_lds_dwordx4 v130, s[96:97]
	ds_read_b128 v[210:213], v135 offset:49152
	ds_read_b128 v[214:217], v139 offset:49152
	ds_read_b128 v[218:221], v135 offset:51200
	ds_read_b128 v[222:225], v139 offset:51200
	s_waitcnt vmcnt(8) lgkmcnt(0)
	s_barrier
	s_setprio 1
	s_waitcnt lgkmcnt(7)
	v_mfma_f32_16x16x32_bf16 v[124:127], v[142:145], v[178:181], v[124:127]
	v_mfma_f32_16x16x32_bf16 v[120:123], v[170:173], v[178:181], v[120:123]
	s_waitcnt lgkmcnt(5)
	v_mfma_f32_16x16x32_bf16 v[116:119], v[142:145], v[186:189], v[116:119]
	v_mfma_f32_16x16x32_bf16 v[112:115], v[170:173], v[186:189], v[112:115]
	s_waitcnt lgkmcnt(3)
	v_mfma_f32_16x16x32_bf16 v[108:111], v[142:145], v[194:197], v[108:111]
	v_mfma_f32_16x16x32_bf16 v[104:107], v[170:173], v[194:197], v[104:107]
	s_waitcnt lgkmcnt(1)
	v_mfma_f32_16x16x32_bf16 v[100:103], v[142:145], v[202:205], v[100:103]
	v_mfma_f32_16x16x32_bf16 v[96:99], v[170:173], v[202:205], v[96:99]
	v_mfma_f32_16x16x32_bf16 v[124:127], v[166:169], v[182:185], v[124:127]
	v_mfma_f32_16x16x32_bf16 v[120:123], v[174:177], v[182:185], v[120:123]
	v_mfma_f32_16x16x32_bf16 v[116:119], v[166:169], v[190:193], v[116:119]
	v_mfma_f32_16x16x32_bf16 v[112:115], v[174:177], v[190:193], v[112:115]
	v_mfma_f32_16x16x32_bf16 v[108:111], v[166:169], v[198:201], v[108:111]
	v_mfma_f32_16x16x32_bf16 v[104:107], v[174:177], v[198:201], v[104:107]
	s_waitcnt lgkmcnt(0)
	v_mfma_f32_16x16x32_bf16 v[100:103], v[166:169], v[206:209], v[100:103]
	v_mfma_f32_16x16x32_bf16 v[96:99], v[174:177], v[206:209], v[96:99]
	s_setprio 0
	s_setprio 1
	s_waitcnt lgkmcnt(3)
	v_mfma_f32_16x16x32_bf16 v[92:95], v[210:213], v[178:181], v[92:95]
	s_waitcnt lgkmcnt(1)
	v_mfma_f32_16x16x32_bf16 v[88:91], v[218:221], v[178:181], v[88:91]
	v_mfma_f32_16x16x32_bf16 v[84:87], v[210:213], v[186:189], v[84:87]
	v_mfma_f32_16x16x32_bf16 v[80:83], v[218:221], v[186:189], v[80:83]
	v_mfma_f32_16x16x32_bf16 v[76:79], v[210:213], v[194:197], v[76:79]
	v_mfma_f32_16x16x32_bf16 v[72:75], v[218:221], v[194:197], v[72:75]
	v_mfma_f32_16x16x32_bf16 v[68:71], v[210:213], v[202:205], v[68:71]
	v_mfma_f32_16x16x32_bf16 v[64:67], v[218:221], v[202:205], v[64:67]
	v_mfma_f32_16x16x32_bf16 v[92:95], v[214:217], v[182:185], v[92:95]
	s_waitcnt lgkmcnt(0)
	v_mfma_f32_16x16x32_bf16 v[88:91], v[222:225], v[182:185], v[88:91]
	v_mfma_f32_16x16x32_bf16 v[84:87], v[214:217], v[190:193], v[84:87]
	v_mfma_f32_16x16x32_bf16 v[80:83], v[222:225], v[190:193], v[80:83]
	v_mfma_f32_16x16x32_bf16 v[76:79], v[214:217], v[198:201], v[76:79]
	v_mfma_f32_16x16x32_bf16 v[72:75], v[222:225], v[198:201], v[72:75]
	v_mfma_f32_16x16x32_bf16 v[68:71], v[214:217], v[206:209], v[68:71]
	v_mfma_f32_16x16x32_bf16 v[64:67], v[222:225], v[206:209], v[64:67]
	s_setprio 0
	s_barrier
; template <int N, int K, int EPI>
; __device__ void gemm_phase(const u16* __restrict__ A, const u16* __restrict__ Bt, const EpiArgs ea, char* smem, int tid) {
;     ...
;     for (int t = 0; t < nt; t += 2) {
;       const bool lastit = (t == nt - 2);
;       const u16* A2 = lastit ? Abn : Ab;
;       const u16* B2 = lastit ? Bbn : Bb;
;       const int k2 = lastit ? 0 : t + 2;
;       BODY(Ab, t + 1, A2, B2, k2, k2 + 1);
	s_or_b32 s70, s70, 64
	s_add_u32 s92, s12, 0x80
	s_addc_u32 s93, s13, 0
	s_add_u32 s12, s12, 0x58080
	s_mov_b32 m0, s27
	s_nop 0
	global_load_lds_dwordx4 v130, s[92:93]
	s_addc_u32 s13, s13, 0
	s_mov_b32 m0, s28
	s_nop 0
	global_load_lds_dwordx4 v130, s[12:13]
	ds_read_b128 v[178:181], v136 offset:49152
	ds_read_b128 v[182:185], v137 offset:49152
	ds_read_b128 v[186:189], v136 offset:51200
	ds_read_b128 v[190:193], v137 offset:51200
	ds_read_b128 v[194:197], v136 offset:53248
	ds_read_b128 v[198:201], v137 offset:53248
	ds_read_b128 v[202:205], v136 offset:55296
	ds_read_b128 v[206:209], v137 offset:55296
	s_add_u32 s12, s14, 0x80
	s_addc_u32 s13, s15, 0
	s_add_u32 s14, s14, 0x58080
	s_mov_b32 m0, s29
	s_nop 0
	global_load_lds_dwordx4 v130, s[12:13]
	s_addc_u32 s15, s15, 0
	s_mov_b32 m0, s30
	s_nop 0
	global_load_lds_dwordx4 v130, s[14:15]
	s_lshl_b64 s[12:13], s[70:71], 1
	s_add_u32 s12, s83, s12
	s_addc_u32 s13, s82, s13
	s_add_u32 s14, s12, 0x58000
	s_mov_b32 m0, s31
	s_nop 0
	global_load_lds_dwordx4 v130, s[12:13]
	s_addc_u32 s15, s13, 0
	s_mov_b32 m0, s34
	s_nop 0
	global_load_lds_dwordx4 v130, s[14:15]
	s_waitcnt vmcnt(8) lgkmcnt(0)
	s_barrier
	s_setprio 1
	s_waitcnt lgkmcnt(7)
	v_mfma_f32_16x16x32_bf16 v[60:63], v[142:145], v[178:181], v[60:63]
	v_mfma_f32_16x16x32_bf16 v[56:59], v[170:173], v[178:181], v[56:59]
	s_waitcnt lgkmcnt(5)
	v_mfma_f32_16x16x32_bf16 v[52:55], v[142:145], v[186:189], v[52:55]
	v_mfma_f32_16x16x32_bf16 v[48:51], v[170:173], v[186:189], v[48:51]
	s_waitcnt lgkmcnt(3)
	v_mfma_f32_16x16x32_bf16 v[44:47], v[142:145], v[194:197], v[44:47]
	v_mfma_f32_16x16x32_bf16 v[40:43], v[170:173], v[194:197], v[40:43]
	s_waitcnt lgkmcnt(1)
	v_mfma_f32_16x16x32_bf16 v[36:39], v[142:145], v[202:205], v[36:39]
	v_mfma_f32_16x16x32_bf16 v[32:35], v[170:173], v[202:205], v[32:35]
	v_mfma_f32_16x16x32_bf16 v[60:63], v[166:169], v[182:185], v[60:63]
	v_mfma_f32_16x16x32_bf16 v[56:59], v[174:177], v[182:185], v[56:59]
	v_mfma_f32_16x16x32_bf16 v[52:55], v[166:169], v[190:193], v[52:55]
	v_mfma_f32_16x16x32_bf16 v[48:51], v[174:177], v[190:193], v[48:51]
	v_mfma_f32_16x16x32_bf16 v[44:47], v[166:169], v[198:201], v[44:47]
	v_mfma_f32_16x16x32_bf16 v[40:43], v[174:177], v[198:201], v[40:43]
	s_waitcnt lgkmcnt(0)
	v_mfma_f32_16x16x32_bf16 v[36:39], v[166:169], v[206:209], v[36:39]
	v_mfma_f32_16x16x32_bf16 v[32:35], v[174:177], v[206:209], v[32:35]
	s_setprio 0
	s_setprio 1
	v_mfma_f32_16x16x32_bf16 v[28:31], v[210:213], v[178:181], v[28:31]
	v_mfma_f32_16x16x32_bf16 v[24:27], v[218:221], v[178:181], v[24:27]
	v_mfma_f32_16x16x32_bf16 v[20:23], v[210:213], v[186:189], v[20:23]
	v_mfma_f32_16x16x32_bf16 v[16:19], v[218:221], v[186:189], v[16:19]
	v_mfma_f32_16x16x32_bf16 v[12:15], v[210:213], v[194:197], v[12:15]
	v_mfma_f32_16x16x32_bf16 v[8:11], v[218:221], v[194:197], v[8:11]
	v_mfma_f32_16x16x32_bf16 v[4:7], v[210:213], v[202:205], v[4:7]
	v_mfma_f32_16x16x32_bf16 v[0:3], v[218:221], v[202:205], v[0:3]
	v_mfma_f32_16x16x32_bf16 v[28:31], v[214:217], v[182:185], v[28:31]
	v_mfma_f32_16x16x32_bf16 v[24:27], v[222:225], v[182:185], v[24:27]
	v_mfma_f32_16x16x32_bf16 v[20:23], v[214:217], v[190:193], v[20:23]
	v_mfma_f32_16x16x32_bf16 v[16:19], v[222:225], v[190:193], v[16:19]
	v_mfma_f32_16x16x32_bf16 v[12:15], v[214:217], v[198:201], v[12:15]
	v_mfma_f32_16x16x32_bf16 v[8:11], v[222:225], v[198:201], v[8:11]
	v_mfma_f32_16x16x32_bf16 v[4:7], v[214:217], v[206:209], v[4:7]
	v_mfma_f32_16x16x32_bf16 v[0:3], v[222:225], v[206:209], v[0:3]
	s_setprio 0
	s_add_i32 s89, s89, 2
	s_addk_i32 s94, 0x80
	s_add_u32 s10, s10, 0x100
	s_addc_u32 s11, s11, 0
	s_cmp_gt_u32 s89, 41
	s_barrier
	s_cbranch_scc0 .LBB0_220
; #define WAIT_V(n) asm volatile("s_waitcnt vmcnt(" #n ")" ::: "memory")
; #define BAR __builtin_amdgcn_s_barrier()
; template <int N, int K, int EPI>
; __device__ void gemm_phase(const u16* __restrict__ A, const u16* __restrict__ Bt, const EpiArgs ea, char* smem, int tid) {
;     ...
;         u16* f = ea.o0;
; #pragma unroll
;         for (int ai = 0; ai < 2; ++ai)
; #pragma unroll
;           for (int bj = 0; bj < 2; ++bj)
; #pragma unroll
;             for (int m = 0; m < 4; ++m) {
;               const int row = brow + ai * HALF + wr * 64 + m * 16 + fr_e;
;               const int col = pn * BM + bj * HALF + wc * 32 + fq_e * 8;
;               const f32x4 v0 = acc[ai][bj][m][0], v1 = acc[ai][bj][m][1];
;               u32x4 o = {pk_bf16(v0[0], v0[1]), pk_bf16(v0[2], v0[3]), pk_bf16(v1[0], v1[1]), pk_bf16(v1[2], v1[3])};
;               *(u32x4*)(f + (size_t)row * N + col) = o;
;             }
;     ...
;   WAIT_V(0);
;   if (wr == 0) BAR;
	s_lshl_b32 s6, s88, 8
	v_mov_b32_e32 v128, v131
	v_mov_b32_e32 v129, v132
	s_add_i32 s6, s6, s35
	v_cvt_pk_bf16_f32 v124, v124, v125
	v_cvt_pk_bf16_f32 v125, v126, v127
	v_cvt_pk_bf16_f32 v126, v120, v121
	v_cvt_pk_bf16_f32 v127, v122, v123
	v_cvt_pk_bf16_f32 v116, v116, v117
	s_nop 0
	v_add_u32_e32 v142, s6, v128
	s_lshl_b32 s6, s73, 8
	s_or_b32 s6, s6, s42
	v_lshl_add_u32 v144, v129, 3, s6
	v_ashrrev_i32_e32 v145, 31, v144
	v_ashrrev_i32_e32 v143, 31, v142
	v_lshl_add_u64 v[128:129], v[144:145], 1, s[64:65]
	v_lshlrev_b64 v[120:121], 11, v[142:143]
	v_lshl_add_u64 v[122:123], v[128:129], 0, v[120:121]
	global_store_dwordx4 v[122:123], v[124:127], off
	v_add_u32_e32 v122, 16, v142
	v_ashrrev_i32_e32 v123, 31, v122
	v_cvt_pk_bf16_f32 v117, v118, v119
	v_cvt_pk_bf16_f32 v118, v112, v113
	v_lshlrev_b64 v[112:113], 11, v[122:123]
	v_cvt_pk_bf16_f32 v119, v114, v115
	v_lshl_add_u64 v[114:115], v[128:129], 0, v[112:113]
	global_store_dwordx4 v[114:115], v[116:119], off
	v_add_u32_e32 v114, 32, v142
	v_ashrrev_i32_e32 v115, 31, v114
	v_cvt_pk_bf16_f32 v108, v108, v109
	v_cvt_pk_bf16_f32 v109, v110, v111
	v_cvt_pk_bf16_f32 v110, v104, v105
	v_lshlrev_b64 v[104:105], 11, v[114:115]
	v_cvt_pk_bf16_f32 v111, v106, v107
	v_lshl_add_u64 v[106:107], v[128:129], 0, v[104:105]
	global_store_dwordx4 v[106:107], v[108:111], off
	v_add_u32_e32 v106, 48, v142
	v_ashrrev_i32_e32 v107, 31, v106
	v_cvt_pk_bf16_f32 v100, v100, v101
	v_cvt_pk_bf16_f32 v101, v102, v103
	v_cvt_pk_bf16_f32 v102, v96, v97
	v_lshlrev_b64 v[96:97], 11, v[106:107]
	v_cvt_pk_bf16_f32 v103, v98, v99
	v_lshl_add_u64 v[98:99], v[128:129], 0, v[96:97]
	global_store_dwordx4 v[98:99], v[100:103], off
	v_add_u32_e32 v98, 0x80, v144
	v_ashrrev_i32_e32 v99, 31, v98
	v_lshl_add_u64 v[98:99], v[98:99], 1, s[64:65]
	v_cvt_pk_bf16_f32 v68, v68, v69
	v_cvt_pk_bf16_f32 v69, v70, v71
	v_cvt_pk_bf16_f32 v70, v64, v65
	v_lshl_add_u64 v[64:65], v[98:99], 0, v[96:97]
	v_cvt_pk_bf16_f32 v71, v66, v67
	global_store_dwordx4 v[64:65], v[68:71], off
	v_add_u32_e32 v64, 0x80, v142
	v_ashrrev_i32_e32 v65, 31, v64
	v_cvt_pk_bf16_f32 v60, v60, v61
	v_cvt_pk_bf16_f32 v61, v62, v63
	v_cvt_pk_bf16_f32 v62, v56, v57
	v_lshlrev_b64 v[56:57], 11, v[64:65]
	v_cvt_pk_bf16_f32 v92, v92, v93
	v_cvt_pk_bf16_f32 v93, v94, v95
	v_cvt_pk_bf16_f32 v94, v88, v89
	v_lshl_add_u64 v[88:89], v[98:99], 0, v[120:121]
	v_cvt_pk_bf16_f32 v84, v84, v85
	v_cvt_pk_bf16_f32 v85, v86, v87
	v_cvt_pk_bf16_f32 v86, v80, v81
	v_lshl_add_u64 v[80:81], v[98:99], 0, v[112:113]
	v_cvt_pk_bf16_f32 v76, v76, v77
	v_cvt_pk_bf16_f32 v77, v78, v79
	v_cvt_pk_bf16_f32 v78, v72, v73
	v_lshl_add_u64 v[72:73], v[98:99], 0, v[104:105]
	v_cvt_pk_bf16_f32 v63, v58, v59
	v_lshl_add_u64 v[58:59], v[128:129], 0, v[56:57]
	v_cvt_pk_bf16_f32 v95, v90, v91
	global_store_dwordx4 v[88:89], v[92:95], off
	v_cvt_pk_bf16_f32 v87, v82, v83
	global_store_dwordx4 v[80:81], v[84:87], off
	v_cvt_pk_bf16_f32 v79, v74, v75
	global_store_dwordx4 v[72:73], v[76:79], off
	global_store_dwordx4 v[58:59], v[60:63], off
	v_add_u32_e32 v58, 0x90, v142
	v_ashrrev_i32_e32 v59, 31, v58
	v_cvt_pk_bf16_f32 v52, v52, v53
	v_cvt_pk_bf16_f32 v53, v54, v55
	v_cvt_pk_bf16_f32 v54, v48, v49
	v_lshlrev_b64 v[48:49], 11, v[58:59]
	v_cvt_pk_bf16_f32 v55, v50, v51
	v_lshl_add_u64 v[50:51], v[128:129], 0, v[48:49]
	global_store_dwordx4 v[50:51], v[52:55], off
	v_add_u32_e32 v50, 0xa0, v142
	v_ashrrev_i32_e32 v51, 31, v50
	v_cvt_pk_bf16_f32 v44, v44, v45
	v_cvt_pk_bf16_f32 v45, v46, v47
	v_cvt_pk_bf16_f32 v46, v40, v41
	v_lshlrev_b64 v[40:41], 11, v[50:51]
	v_cvt_pk_bf16_f32 v47, v42, v43
	v_lshl_add_u64 v[42:43], v[128:129], 0, v[40:41]
	global_store_dwordx4 v[42:43], v[44:47], off
	v_add_u32_e32 v42, 0xb0, v142
	v_ashrrev_i32_e32 v43, 31, v42
	v_cvt_pk_bf16_f32 v36, v36, v37
	v_cvt_pk_bf16_f32 v37, v38, v39
	v_cvt_pk_bf16_f32 v38, v32, v33
	v_lshlrev_b64 v[32:33], 11, v[42:43]
	v_cvt_pk_bf16_f32 v39, v34, v35
	v_lshl_add_u64 v[34:35], v[128:129], 0, v[32:33]
	v_cvt_pk_bf16_f32 v28, v28, v29
	v_cvt_pk_bf16_f32 v29, v30, v31
	v_cvt_pk_bf16_f32 v30, v24, v25
	v_lshl_add_u64 v[24:25], v[98:99], 0, v[56:57]
	v_cvt_pk_bf16_f32 v20, v20, v21
	v_cvt_pk_bf16_f32 v21, v22, v23
	v_cvt_pk_bf16_f32 v22, v16, v17
	v_lshl_add_u64 v[16:17], v[98:99], 0, v[48:49]
	v_cvt_pk_bf16_f32 v12, v12, v13
	v_cvt_pk_bf16_f32 v13, v14, v15
	v_cvt_pk_bf16_f32 v14, v8, v9
	v_lshl_add_u64 v[8:9], v[98:99], 0, v[40:41]
	v_cvt_pk_bf16_f32 v4, v4, v5
	v_cvt_pk_bf16_f32 v5, v6, v7
	v_cvt_pk_bf16_f32 v6, v0, v1
	v_lshl_add_u64 v[0:1], v[98:99], 0, v[32:33]
	s_and_b64 vcc, exec, s[0:1]
	s_mov_b32 s88, s67
	s_mov_b32 s73, s72
	s_mov_b64 s[8:9], s[4:5]
	s_mov_b64 s[6:7], s[2:3]
	global_store_dwordx4 v[34:35], v[36:39], off
	v_cvt_pk_bf16_f32 v31, v26, v27
	global_store_dwordx4 v[24:25], v[28:31], off
	v_cvt_pk_bf16_f32 v23, v18, v19
	global_store_dwordx4 v[16:17], v[20:23], off
	v_cvt_pk_bf16_f32 v15, v10, v11
	global_store_dwordx4 v[8:9], v[12:15], off
	v_cvt_pk_bf16_f32 v7, v2, v3
	global_store_dwordx4 v[0:1], v[4:7], off
	s_cbranch_vccz .LBB0_217
	s_waitcnt vmcnt(0)
	v_readlane_b32 s34, v226, 32
	v_readlane_b32 s36, v226, 30
	s_cmpk_gt_u32 s18, 0xff
	s_movk_i32 s27, 0x7fff
	s_mov_b32 s28, 0x800000
	s_mov_b32 s29, 0xa000000
	s_mov_b32 s30, 0x41000
	v_readlane_b32 s35, v226, 33
	v_readlane_b32 s37, v226, 31
	s_cbranch_scc1 .LBB0_224
	s_barrier

; #define WAIT_V(n) asm volatile("s_waitcnt vmcnt(" #n ")" ::: "memory")
; #define BAR __builtin_amdgcn_s_barrier()
; template <int N, int K, int EPI>
; __device__ void gemm_phase(const u16* __restrict__ A, const u16* __restrict__ Bt, const EpiArgs ea, char* smem, int tid) {
;     ...
;   const int wid = __builtin_amdgcn_readfirstlane(tidl >> 6);
;   const int lane = tidl & 63, wr = wid >> 2, wc = wid & 3, fr = lane & 15, fq = lane >> 4;
;   const int tb = tidl * 16;
;   unsigned off0b;
;   { int R, C; stage_rc((tidl & 63) * 16 + wid * 1024, R, C); off0b = (unsigned)(R * K + C) * 2u; }
;   const unsigned lds0 = (unsigned)(size_t)(__attribute__((address_space(3))) char*)smem;
;   int pm, pn; tile_map(v, nN, pm, pn);
;   const u16* Ab = A + (size_t)pm * BM * K;
;   const u16* Bb = Bt + (size_t)pn * BM * K;
;   f32x4 acc[2][2][4][2] = {};
;   bf16x8 At[4][2], B0[2][2], B1[2][2];
;   STAGE(SB(0, 0), GP(Bb, 0, 0)); STAGE(SA(0, 0), GP(Ab, 0, 0));
;   STAGE(SB(0, 1), GP(Bb, 1, 0)); STAGE(SA(0, 1), GP(Ab, 1, 0));
;   if (wr == 1) BAR;
;   WAIT_V(4); BAR;
;   STAGE(SB(1, 0), GP(Bb, 0, 1)); STAGE(SA(1, 0), GP(Ab, 0, 1)); STAGE(SB(1, 1), GP(Bb, 1, 1));
;   WAIT_V(6); BAR;
.LBB0_232:
	s_and_b32 s18, s2, 3
	s_add_u32 s2, s12, 0x80
	s_addc_u32 s3, s13, 0
	s_add_u32 s4, s12, 0x20080
	s_addc_u32 s5, s13, 0
	s_add_u32 s6, s10, 0x80
	s_addc_u32 s7, s11, 0
	s_add_u32 s8, s10, 0x20080
	s_addc_u32 s9, s11, 0
	s_add_u32 s14, s12, 0x40080
	s_addc_u32 s15, s13, 0
	s_add_u32 s16, s12, 0x60080
	v_readlane_b32 s19, v227, 60
	s_addc_u32 s17, s13, 0
	s_waitcnt vmcnt(2)
	s_barrier
	s_add_i32 s31, s1, s19
	s_mov_b32 m0, s31
	s_nop 0
	global_load_lds_dwordx4 v130, s[2:3]
	v_and_b32_e32 v131, 15, v0
	s_add_i32 s34, s23, 0x1a000
	s_mov_b32 m0, s34
	s_nop 0
	global_load_lds_dwordx4 v130, s[4:5]
	v_lshlrev_b32_e32 v3, 2, v0
	v_lshrrev_b32_e32 v132, 4, v1
	s_add_i32 s35, s23, 0x8000
	s_mov_b32 m0, s35
	s_nop 0
	global_load_lds_dwordx4 v130, s[6:7]
	v_and_b32_e32 v1, 48, v0
	v_lshlrev_b32_e32 v2, 6, v131
	v_and_b32_e32 v3, 32, v3
	s_add_i32 s36, s23, 0xa000
	s_mov_b32 m0, s36
	s_nop 0
	global_load_lds_dwordx4 v130, s[8:9]
	v_readlane_b32 s3, v227, 61
	v_bitop3_b32 v2, v2, v3, v1 bitop3:0x36
	s_add_i32 s2, 0, 0x10000
	s_add_i32 s37, s1, s3
	s_mov_b32 m0, s37
	s_nop 0
	global_load_lds_dwordx4 v130, s[14:15]
	v_add_u32_e32 v4, s2, v2
	s_add_i32 s2, 0, 0x14000
	s_add_i32 s42, s23, 0x1e000
	s_mov_b32 m0, s42
	s_nop 0
	global_load_lds_dwordx4 v130, s[16:17]
	v_add_u32_e32 v5, s2, v2
	v_lshlrev_b32_e32 v0, 6, v0
	s_movk_i32 s2, 0x3c0
	s_waitcnt vmcnt(6)
	s_lshl_b32 s1, s18, 12
	s_lshl_b32 s43, s0, 6
	v_add_u32_e32 v6, s19, v2
	v_add_u32_e32 v7, s3, v2
	s_lshl_b32 s0, s0, 13
	v_add_u32_e32 v2, 0, v2
	v_and_or_b32 v0, v0, s2, v1
	v_xad_u32 v134, v0, v3, 0
	s_or_b32 s67, s0, 0x800
	s_or_b32 s2, s0, 0x1000
	s_or_b32 s3, s0, 0x1800
	v_add_u32_e32 v135, s1, v4
	v_add_u32_e32 v136, s0, v2
	v_add_u32_e32 v139, s1, v5
	v_add_u32_e32 v140, s1, v6
	v_add_u32_e32 v141, s1, v7
	v_readlane_b32 s0, v227, 31
	s_add_i32 s64, s23, 0xc000
	s_add_i32 s65, s23, 0xe000
	s_lshl_b32 s66, s18, 5
	v_add_u32_e32 v137, s2, v134
	v_add_u32_e32 v138, s3, v134
	s_mov_b32 s77, s0
	v_readlane_b32 s73, v227, 30
	s_mov_b32 s72, s94
	s_barrier
	v_readlane_b32 s1, v227, 32
	v_and_b32_e32 v120, 15, v164
	v_bfe_u32 v121, v164, 4, 2
	v_lshrrev_b32_e32 v122, 3, v120
	v_and_b32_e32 v123, 7, v120
	v_lshlrev_b32_e32 v124, 10, v122
	v_lshl_add_u32 v124, v123, 7, v124
	v_lshl_add_u32 v124, v122, 6, v124
	v_bfe_u32 v125, v120, 1, 2
	v_xor_b32_e32 v125, v125, v121
	v_lshl_add_u32 v124, v125, 4, v124
	v_lshrrev_b32_e32 v126, 8, v164
	v_lshl_add_u32 v136, v126, 13, v124
	v_xor_b32_e32 v137, 64, v136
	v_bfe_u32 v126, v164, 6, 2
	v_lshl_add_u32 v126, v126, 12, v124
	v_add_u32_e32 v135, 0x10000, v126
	v_xor_b32_e32 v139, 64, v135

.LBB0_236:
	ds_read_b128 v[142:145], v135
	ds_read_b128 v[166:169], v139
	ds_read_b128 v[170:173], v135 offset:2048
	ds_read_b128 v[174:177], v139 offset:2048
	s_add_u32 s16, s14, 0x40080
	s_addc_u32 s17, s15, 0
	s_add_u32 s18, s14, 0x60080
	s_addc_u32 s19, s15, 0
	s_cmp_eq_u32 s3, 12
	s_cselect_b32 s82, s9, s13
	s_cselect_b32 s83, s8, s12
	s_cselect_b32 s92, s7, s11
	s_cselect_b32 s93, s6, s10
	s_nop 0
	ds_read_b128 v[178:181], v136
	ds_read_b128 v[182:185], v137
	ds_read_b128 v[186:189], v136 offset:2048
	ds_read_b128 v[190:193], v137 offset:2048
	ds_read_b128 v[194:197], v136 offset:4096
	ds_read_b128 v[198:201], v137 offset:4096
	ds_read_b128 v[202:205], v136 offset:6144
	ds_read_b128 v[206:209], v137 offset:6144
	s_mov_b32 m0, s64
	s_nop 0
	global_load_lds_dwordx4 v130, s[16:17]
	s_nop 0
	s_mov_b32 m0, s65
	s_nop 0
	global_load_lds_dwordx4 v130, s[18:19]
	ds_read_b128 v[210:213], v135 offset:16384
	ds_read_b128 v[214:217], v139 offset:16384
	ds_read_b128 v[218:221], v135 offset:18432
	ds_read_b128 v[222:225], v139 offset:18432
	s_waitcnt vmcnt(8) lgkmcnt(0)
	s_barrier
	s_setprio 1
	s_waitcnt lgkmcnt(7)
	v_mfma_f32_16x16x32_bf16 v[124:127], v[142:145], v[178:181], v[124:127]
	v_mfma_f32_16x16x32_bf16 v[116:119], v[170:173], v[178:181], v[116:119]
	s_waitcnt lgkmcnt(5)
	v_mfma_f32_16x16x32_bf16 v[108:111], v[142:145], v[186:189], v[108:111]
	v_mfma_f32_16x16x32_bf16 v[100:103], v[170:173], v[186:189], v[100:103]
	s_waitcnt lgkmcnt(3)
	v_mfma_f32_16x16x32_bf16 v[92:95], v[142:145], v[194:197], v[92:95]
	v_mfma_f32_16x16x32_bf16 v[84:87], v[170:173], v[194:197], v[84:87]
	s_waitcnt lgkmcnt(1)
	v_mfma_f32_16x16x32_bf16 v[76:79], v[142:145], v[202:205], v[76:79]
	v_mfma_f32_16x16x32_bf16 v[68:71], v[170:173], v[202:205], v[68:71]
	v_mfma_f32_16x16x32_bf16 v[124:127], v[166:169], v[182:185], v[124:127]
	v_mfma_f32_16x16x32_bf16 v[116:119], v[174:177], v[182:185], v[116:119]
	v_mfma_f32_16x16x32_bf16 v[108:111], v[166:169], v[190:193], v[108:111]
	v_mfma_f32_16x16x32_bf16 v[100:103], v[174:177], v[190:193], v[100:103]
	v_mfma_f32_16x16x32_bf16 v[92:95], v[166:169], v[198:201], v[92:95]
	v_mfma_f32_16x16x32_bf16 v[84:87], v[174:177], v[198:201], v[84:87]
	s_waitcnt lgkmcnt(0)
	v_mfma_f32_16x16x32_bf16 v[76:79], v[166:169], v[206:209], v[76:79]
	v_mfma_f32_16x16x32_bf16 v[68:71], v[174:177], v[206:209], v[68:71]
	s_setprio 0
	s_setprio 1
	s_waitcnt lgkmcnt(3)
	v_mfma_f32_16x16x32_bf16 v[120:123], v[210:213], v[178:181], v[120:123]
	s_waitcnt lgkmcnt(1)
	v_mfma_f32_16x16x32_bf16 v[112:115], v[218:221], v[178:181], v[112:115]
	v_mfma_f32_16x16x32_bf16 v[104:107], v[210:213], v[186:189], v[104:107]
	v_mfma_f32_16x16x32_bf16 v[96:99], v[218:221], v[186:189], v[96:99]
	v_mfma_f32_16x16x32_bf16 v[88:91], v[210:213], v[194:197], v[88:91]
	v_mfma_f32_16x16x32_bf16 v[80:83], v[218:221], v[194:197], v[80:83]
	v_mfma_f32_16x16x32_bf16 v[72:75], v[210:213], v[202:205], v[72:75]
	v_mfma_f32_16x16x32_bf16 v[64:67], v[218:221], v[202:205], v[64:67]
	v_mfma_f32_16x16x32_bf16 v[120:123], v[214:217], v[182:185], v[120:123]
	s_waitcnt lgkmcnt(0)
	v_mfma_f32_16x16x32_bf16 v[112:115], v[222:225], v[182:185], v[112:115]
	v_mfma_f32_16x16x32_bf16 v[104:107], v[214:217], v[190:193], v[104:107]
	v_mfma_f32_16x16x32_bf16 v[96:99], v[222:225], v[190:193], v[96:99]
	v_mfma_f32_16x16x32_bf16 v[88:91], v[214:217], v[198:201], v[88:91]
	v_mfma_f32_16x16x32_bf16 v[80:83], v[222:225], v[198:201], v[80:83]
	v_mfma_f32_16x16x32_bf16 v[72:75], v[214:217], v[206:209], v[72:75]
	v_mfma_f32_16x16x32_bf16 v[64:67], v[222:225], v[206:209], v[64:67]
	s_setprio 0
	s_barrier
	s_cselect_b32 s70, 0, s5
	s_lshl_b64 s[88:89], s[70:71], 1
	s_add_u32 s16, s83, s88
	s_addc_u32 s17, s82, s89
	s_add_u32 s18, s16, 0x20000
	s_mov_b32 m0, s24
	s_nop 0
	global_load_lds_dwordx4 v130, s[16:17]
	s_addc_u32 s19, s17, 0
	s_mov_b32 m0, s25
	s_nop 0
	global_load_lds_dwordx4 v130, s[18:19]
	ds_read_b128 v[178:181], v136 offset:16384
	ds_read_b128 v[182:185], v137 offset:16384
	ds_read_b128 v[186:189], v136 offset:18432
	ds_read_b128 v[190:193], v137 offset:18432
	ds_read_b128 v[194:197], v136 offset:20480
	ds_read_b128 v[198:201], v137 offset:20480
	ds_read_b128 v[202:205], v136 offset:22528
	ds_read_b128 v[206:209], v137 offset:22528
	s_add_u32 s18, s93, s88
	s_addc_u32 s19, s92, s89
	s_add_u32 s94, s18, 0x20000
	s_mov_b32 m0, s23
	s_nop 0
	global_load_lds_dwordx4 v130, s[18:19]
	s_addc_u32 s95, s19, 0
	s_mov_b32 m0, s26
	s_nop 0
	global_load_lds_dwordx4 v130, s[94:95]
	s_add_u32 s83, s83, 0x40000
	s_addc_u32 s82, s82, 0
	s_add_u32 s88, s83, s88
	s_addc_u32 s89, s82, s89
	s_add_u32 s94, s88, 0x20000
	s_mov_b32 m0, s27
	s_nop 0
	global_load_lds_dwordx4 v130, s[88:89]
	s_addc_u32 s95, s89, 0
	s_mov_b32 m0, s28
	s_nop 0
	global_load_lds_dwordx4 v130, s[94:95]
	s_waitcnt vmcnt(8) lgkmcnt(0)
	s_barrier
	s_setprio 1
	s_waitcnt lgkmcnt(7)
	v_mfma_f32_16x16x32_bf16 v[60:63], v[142:145], v[178:181], v[60:63]
	v_mfma_f32_16x16x32_bf16 v[52:55], v[170:173], v[178:181], v[52:55]
	s_waitcnt lgkmcnt(5)
	v_mfma_f32_16x16x32_bf16 v[44:47], v[142:145], v[186:189], v[44:47]
	v_mfma_f32_16x16x32_bf16 v[36:39], v[170:173], v[186:189], v[36:39]
	s_waitcnt lgkmcnt(3)
	v_mfma_f32_16x16x32_bf16 v[28:31], v[142:145], v[194:197], v[28:31]
	v_mfma_f32_16x16x32_bf16 v[20:23], v[170:173], v[194:197], v[20:23]
	s_waitcnt lgkmcnt(1)
	v_mfma_f32_16x16x32_bf16 v[12:15], v[142:145], v[202:205], v[12:15]
	v_mfma_f32_16x16x32_bf16 v[4:7], v[170:173], v[202:205], v[4:7]
	v_mfma_f32_16x16x32_bf16 v[60:63], v[166:169], v[182:185], v[60:63]
	v_mfma_f32_16x16x32_bf16 v[52:55], v[174:177], v[182:185], v[52:55]
	v_mfma_f32_16x16x32_bf16 v[44:47], v[166:169], v[190:193], v[44:47]
	v_mfma_f32_16x16x32_bf16 v[36:39], v[174:177], v[190:193], v[36:39]
	v_mfma_f32_16x16x32_bf16 v[28:31], v[166:169], v[198:201], v[28:31]
	v_mfma_f32_16x16x32_bf16 v[20:23], v[174:177], v[198:201], v[20:23]
	s_waitcnt lgkmcnt(0)
	v_mfma_f32_16x16x32_bf16 v[12:15], v[166:169], v[206:209], v[12:15]
	v_mfma_f32_16x16x32_bf16 v[4:7], v[174:177], v[206:209], v[4:7]
	s_setprio 0
	s_setprio 1
	v_mfma_f32_16x16x32_bf16 v[56:59], v[210:213], v[178:181], v[56:59]
	v_mfma_f32_16x16x32_bf16 v[48:51], v[218:221], v[178:181], v[48:51]
	v_mfma_f32_16x16x32_bf16 v[40:43], v[210:213], v[186:189], v[40:43]
	v_mfma_f32_16x16x32_bf16 v[32:35], v[218:221], v[186:189], v[32:35]
	v_mfma_f32_16x16x32_bf16 v[24:27], v[210:213], v[194:197], v[24:27]
	v_mfma_f32_16x16x32_bf16 v[16:19], v[218:221], v[194:197], v[16:19]
	v_mfma_f32_16x16x32_bf16 v[8:11], v[210:213], v[202:205], v[8:11]
	v_mfma_f32_16x16x32_bf16 v[0:3], v[218:221], v[202:205], v[0:3]
	v_mfma_f32_16x16x32_bf16 v[56:59], v[214:217], v[182:185], v[56:59]
	v_mfma_f32_16x16x32_bf16 v[48:51], v[222:225], v[182:185], v[48:51]
	v_mfma_f32_16x16x32_bf16 v[40:43], v[214:217], v[190:193], v[40:43]
	v_mfma_f32_16x16x32_bf16 v[32:35], v[222:225], v[190:193], v[32:35]
	v_mfma_f32_16x16x32_bf16 v[24:27], v[214:217], v[198:201], v[24:27]
	v_mfma_f32_16x16x32_bf16 v[16:19], v[222:225], v[198:201], v[16:19]
	v_mfma_f32_16x16x32_bf16 v[8:11], v[214:217], v[206:209], v[8:11]
	v_mfma_f32_16x16x32_bf16 v[0:3], v[222:225], v[206:209], v[0:3]
	s_setprio 0
	s_barrier
	ds_read_b128 v[142:145], v135 offset:32768
	ds_read_b128 v[166:169], v139 offset:32768
	ds_read_b128 v[170:173], v135 offset:34816
	ds_read_b128 v[174:177], v139 offset:34816
	ds_read_b128 v[178:181], v136 offset:32768
	ds_read_b128 v[182:185], v137 offset:32768
	ds_read_b128 v[186:189], v136 offset:34816
	ds_read_b128 v[190:193], v137 offset:34816
	ds_read_b128 v[194:197], v136 offset:36864
	ds_read_b128 v[198:201], v137 offset:36864
	ds_read_b128 v[202:205], v136 offset:38912
	ds_read_b128 v[206:209], v137 offset:38912
	s_add_u32 s88, s18, 0x40000
	s_addc_u32 s89, s19, 0
	s_add_u32 s94, s18, 0x60000
	s_mov_b32 m0, s29
	s_nop 0
	global_load_lds_dwordx4 v130, s[88:89]
	s_addc_u32 s95, s19, 0
	s_mov_b32 m0, s30
	s_nop 0
	global_load_lds_dwordx4 v130, s[94:95]
	ds_read_b128 v[210:213], v135 offset:49152
	ds_read_b128 v[214:217], v139 offset:49152
	ds_read_b128 v[218:221], v135 offset:51200
	ds_read_b128 v[222:225], v139 offset:51200
	s_waitcnt vmcnt(8) lgkmcnt(0)
	s_barrier
	s_setprio 1
	s_waitcnt lgkmcnt(7)
	v_mfma_f32_16x16x32_bf16 v[124:127], v[142:145], v[178:181], v[124:127]
	v_mfma_f32_16x16x32_bf16 v[116:119], v[170:173], v[178:181], v[116:119]
	s_waitcnt lgkmcnt(5)
	v_mfma_f32_16x16x32_bf16 v[108:111], v[142:145], v[186:189], v[108:111]
	v_mfma_f32_16x16x32_bf16 v[100:103], v[170:173], v[186:189], v[100:103]
	s_waitcnt lgkmcnt(3)
	v_mfma_f32_16x16x32_bf16 v[92:95], v[142:145], v[194:197], v[92:95]
	v_mfma_f32_16x16x32_bf16 v[84:87], v[170:173], v[194:197], v[84:87]
	s_waitcnt lgkmcnt(1)
	v_mfma_f32_16x16x32_bf16 v[76:79], v[142:145], v[202:205], v[76:79]
	v_mfma_f32_16x16x32_bf16 v[68:71], v[170:173], v[202:205], v[68:71]
	v_mfma_f32_16x16x32_bf16 v[124:127], v[166:169], v[182:185], v[124:127]
	v_mfma_f32_16x16x32_bf16 v[116:119], v[174:177], v[182:185], v[116:119]
	v_mfma_f32_16x16x32_bf16 v[108:111], v[166:169], v[190:193], v[108:111]
	v_mfma_f32_16x16x32_bf16 v[100:103], v[174:177], v[190:193], v[100:103]
	v_mfma_f32_16x16x32_bf16 v[92:95], v[166:169], v[198:201], v[92:95]
	v_mfma_f32_16x16x32_bf16 v[84:87], v[174:177], v[198:201], v[84:87]
	s_waitcnt lgkmcnt(0)
	v_mfma_f32_16x16x32_bf16 v[76:79], v[166:169], v[206:209], v[76:79]
	v_mfma_f32_16x16x32_bf16 v[68:71], v[174:177], v[206:209], v[68:71]
	s_setprio 0
	s_setprio 1
	s_waitcnt lgkmcnt(3)
	v_mfma_f32_16x16x32_bf16 v[120:123], v[210:213], v[178:181], v[120:123]
	s_waitcnt lgkmcnt(1)
	v_mfma_f32_16x16x32_bf16 v[112:115], v[218:221], v[178:181], v[112:115]
	v_mfma_f32_16x16x32_bf16 v[104:107], v[210:213], v[186:189], v[104:107]
	v_mfma_f32_16x16x32_bf16 v[96:99], v[218:221], v[186:189], v[96:99]
	v_mfma_f32_16x16x32_bf16 v[88:91], v[210:213], v[194:197], v[88:91]
	v_mfma_f32_16x16x32_bf16 v[80:83], v[218:221], v[194:197], v[80:83]
	v_mfma_f32_16x16x32_bf16 v[72:75], v[210:213], v[202:205], v[72:75]
	v_mfma_f32_16x16x32_bf16 v[64:67], v[218:221], v[202:205], v[64:67]
	v_mfma_f32_16x16x32_bf16 v[120:123], v[214:217], v[182:185], v[120:123]
	s_waitcnt lgkmcnt(0)
	v_mfma_f32_16x16x32_bf16 v[112:115], v[222:225], v[182:185], v[112:115]
	v_mfma_f32_16x16x32_bf16 v[104:107], v[214:217], v[190:193], v[104:107]
	v_mfma_f32_16x16x32_bf16 v[96:99], v[222:225], v[190:193], v[96:99]
	v_mfma_f32_16x16x32_bf16 v[88:91], v[214:217], v[198:201], v[88:91]
	v_mfma_f32_16x16x32_bf16 v[80:83], v[222:225], v[198:201], v[80:83]
	v_mfma_f32_16x16x32_bf16 v[72:75], v[214:217], v[206:209], v[72:75]
	v_mfma_f32_16x16x32_bf16 v[64:67], v[222:225], v[206:209], v[64:67]
	s_setprio 0
	s_barrier
; template <int N, int K, int EPI>
; __device__ void gemm_phase(const u16* __restrict__ A, const u16* __restrict__ Bt, const EpiArgs ea, char* smem, int tid) {
;     ...
;         for (int ai = 0; ai < 2; ++ai)
; #pragma unroll
;           for (int m = 0; m < 4; ++m) {
;             const int row = brow + ai * HALF + wr * 64 + m * 16 + fr_e;
;             const int col = pn * 128 + wc * 32 + fq_e * 8;
;             u32x4 o;
; #pragma unroll
;             for (int n = 0; n < 2; ++n) {
;               const f32x4 t4 = acc[ai][0][m][n], u4 = acc[ai][1][m][n];
;               f32x2 tl = {t4[0], t4[1]}, th = {t4[2], t4[3]}, ul = {u4[0], u4[1]}, uh = {u4[2], u4[3]};
;               f32x2 el = {__builtin_amdgcn_exp2f(-t4[0]), __builtin_amdgcn_exp2f(-t4[1])};
;               f32x2 eh = {__builtin_amdgcn_exp2f(-t4[2]), __builtin_amdgcn_exp2f(-t4[3])};
;               el = el + 1.f; eh = eh + 1.f;
;               f32x2 rl = {__builtin_amdgcn_rcpf(el[0]), __builtin_amdgcn_rcpf(el[1])};
;               f32x2 rh = {__builtin_amdgcn_rcpf(eh[0]), __builtin_amdgcn_rcpf(eh[1])};
;               const f32x2 hl = tl * ul * rl, hh2 = th * uh * rh;
;               o[2 * n] = pk_bf16(hl[0], hl[1]); o[2 * n + 1] = pk_bf16(hh2[0], hh2[1]);
	s_or_b32 s70, s70, 64
	s_add_u32 s88, s16, 0x80
	s_addc_u32 s89, s17, 0
	s_add_u32 s16, s16, 0x20080
	s_mov_b32 m0, s31
	s_nop 0
	global_load_lds_dwordx4 v130, s[88:89]
	s_addc_u32 s17, s17, 0
	s_mov_b32 m0, s34
	s_nop 0
	global_load_lds_dwordx4 v130, s[16:17]
	ds_read_b128 v[178:181], v136 offset:49152
	ds_read_b128 v[182:185], v137 offset:49152
	ds_read_b128 v[186:189], v136 offset:51200
	ds_read_b128 v[190:193], v137 offset:51200
	ds_read_b128 v[194:197], v136 offset:53248
	ds_read_b128 v[198:201], v137 offset:53248
	ds_read_b128 v[202:205], v136 offset:55296
	ds_read_b128 v[206:209], v137 offset:55296
	s_add_u32 s16, s18, 0x80
	s_addc_u32 s17, s19, 0
	s_add_u32 s18, s18, 0x20080
	s_mov_b32 m0, s35
	s_nop 0
	global_load_lds_dwordx4 v130, s[16:17]
	s_addc_u32 s19, s19, 0
	s_mov_b32 m0, s36
	s_nop 0
	global_load_lds_dwordx4 v130, s[18:19]
	s_lshl_b64 s[16:17], s[70:71], 1
	s_add_u32 s16, s83, s16
	s_addc_u32 s17, s82, s17
	s_add_u32 s18, s16, 0x20000
	s_mov_b32 m0, s37
	s_nop 0
	global_load_lds_dwordx4 v130, s[16:17]
	s_addc_u32 s19, s17, 0
	s_mov_b32 m0, s42
	s_nop 0
	global_load_lds_dwordx4 v130, s[18:19]
	s_waitcnt vmcnt(8) lgkmcnt(0)
	s_barrier
	s_setprio 1
	s_waitcnt lgkmcnt(7)
	v_mfma_f32_16x16x32_bf16 v[60:63], v[142:145], v[178:181], v[60:63]
	v_mfma_f32_16x16x32_bf16 v[52:55], v[170:173], v[178:181], v[52:55]
	s_waitcnt lgkmcnt(5)
	v_mfma_f32_16x16x32_bf16 v[44:47], v[142:145], v[186:189], v[44:47]
	v_mfma_f32_16x16x32_bf16 v[36:39], v[170:173], v[186:189], v[36:39]
	s_waitcnt lgkmcnt(3)
	v_mfma_f32_16x16x32_bf16 v[28:31], v[142:145], v[194:197], v[28:31]
	v_mfma_f32_16x16x32_bf16 v[20:23], v[170:173], v[194:197], v[20:23]
	s_waitcnt lgkmcnt(1)
	v_mfma_f32_16x16x32_bf16 v[12:15], v[142:145], v[202:205], v[12:15]
	v_mfma_f32_16x16x32_bf16 v[4:7], v[170:173], v[202:205], v[4:7]
	v_mfma_f32_16x16x32_bf16 v[60:63], v[166:169], v[182:185], v[60:63]
	v_mfma_f32_16x16x32_bf16 v[52:55], v[174:177], v[182:185], v[52:55]
	v_mfma_f32_16x16x32_bf16 v[44:47], v[166:169], v[190:193], v[44:47]
	v_mfma_f32_16x16x32_bf16 v[36:39], v[174:177], v[190:193], v[36:39]
	v_mfma_f32_16x16x32_bf16 v[28:31], v[166:169], v[198:201], v[28:31]
	v_mfma_f32_16x16x32_bf16 v[20:23], v[174:177], v[198:201], v[20:23]
	s_waitcnt lgkmcnt(0)
	v_mfma_f32_16x16x32_bf16 v[12:15], v[166:169], v[206:209], v[12:15]
	v_mfma_f32_16x16x32_bf16 v[4:7], v[174:177], v[206:209], v[4:7]
	s_setprio 0
	s_setprio 1
	v_mfma_f32_16x16x32_bf16 v[56:59], v[210:213], v[178:181], v[56:59]
	v_mfma_f32_16x16x32_bf16 v[48:51], v[218:221], v[178:181], v[48:51]
	v_mfma_f32_16x16x32_bf16 v[40:43], v[210:213], v[186:189], v[40:43]
	v_mfma_f32_16x16x32_bf16 v[32:35], v[218:221], v[186:189], v[32:35]
	v_mfma_f32_16x16x32_bf16 v[24:27], v[210:213], v[194:197], v[24:27]
	v_mfma_f32_16x16x32_bf16 v[16:19], v[218:221], v[194:197], v[16:19]
	v_mfma_f32_16x16x32_bf16 v[8:11], v[210:213], v[202:205], v[8:11]
	v_mfma_f32_16x16x32_bf16 v[0:3], v[218:221], v[202:205], v[0:3]
	v_mfma_f32_16x16x32_bf16 v[56:59], v[214:217], v[182:185], v[56:59]
	v_mfma_f32_16x16x32_bf16 v[48:51], v[222:225], v[182:185], v[48:51]
	v_mfma_f32_16x16x32_bf16 v[40:43], v[214:217], v[190:193], v[40:43]
	v_mfma_f32_16x16x32_bf16 v[32:35], v[222:225], v[190:193], v[32:35]
	v_mfma_f32_16x16x32_bf16 v[24:27], v[214:217], v[198:201], v[24:27]
	v_mfma_f32_16x16x32_bf16 v[16:19], v[222:225], v[198:201], v[16:19]
	v_mfma_f32_16x16x32_bf16 v[8:11], v[214:217], v[206:209], v[8:11]
	v_mfma_f32_16x16x32_bf16 v[0:3], v[222:225], v[206:209], v[0:3]
	s_setprio 0
	s_add_i32 s3, s3, 2
	s_addk_i32 s5, 0x80
	s_add_u32 s14, s14, 0x100
	s_addc_u32 s15, s15, 0
	s_cmp_gt_u32 s3, 13
	s_barrier
	s_cbranch_scc0 .LBB0_236
	v_exp_f32_e64 v144, -v124
	v_exp_f32_e64 v145, -v125
	v_exp_f32_e64 v146, -v126
	v_exp_f32_e64 v147, -v127
	v_pk_mul_f32 v[122:123], v[126:127], v[122:123]
	v_pk_add_f32 v[144:145], v[144:145], 1.0 op_sel_hi:[1,0]
	v_pk_mul_f32 v[120:121], v[124:125], v[120:121]
	v_pk_add_f32 v[146:147], v[146:147], 1.0 op_sel_hi:[1,0]
	v_rcp_f32_e32 v144, v144
	v_rcp_f32_e32 v145, v145
	v_rcp_f32_e32 v146, v146
	v_rcp_f32_e32 v147, v147
	v_exp_f32_e64 v124, -v116
	v_exp_f32_e64 v125, -v117
	v_exp_f32_e64 v126, -v118
	v_exp_f32_e64 v127, -v119
	v_pk_mul_f32 v[120:121], v[144:145], v[120:121]
	v_pk_mul_f32 v[122:123], v[146:147], v[122:123]
	v_cvt_pk_bf16_f32 v120, v120, v121
	v_pk_mul_f32 v[114:115], v[118:119], v[114:115]
	v_cvt_pk_bf16_f32 v121, v122, v123
	v_pk_add_f32 v[122:123], v[124:125], 1.0 op_sel_hi:[1,0]
	v_pk_add_f32 v[124:125], v[126:127], 1.0 op_sel_hi:[1,0]
	v_rcp_f32_e32 v122, v122
	v_rcp_f32_e32 v123, v123
	v_rcp_f32_e32 v124, v124
	v_rcp_f32_e32 v125, v125
	v_pk_mul_f32 v[112:113], v[116:117], v[112:113]
	v_pk_mul_f32 v[106:107], v[110:111], v[106:107]
	v_pk_mul_f32 v[112:113], v[122:123], v[112:113]
	v_pk_mul_f32 v[114:115], v[124:125], v[114:115]
	v_cvt_pk_bf16_f32 v122, v112, v113
	v_exp_f32_e64 v112, -v108
	v_cvt_pk_bf16_f32 v123, v114, v115
	v_exp_f32_e64 v113, -v109
	v_exp_f32_e64 v114, -v110
	v_exp_f32_e64 v115, -v111
	v_pk_mul_f32 v[104:105], v[108:109], v[104:105]
	v_pk_add_f32 v[112:113], v[112:113], 1.0 op_sel_hi:[1,0]
	v_exp_f32_e64 v108, -v100
	v_pk_add_f32 v[114:115], v[114:115], 1.0 op_sel_hi:[1,0]
	v_rcp_f32_e32 v112, v112
	v_rcp_f32_e32 v113, v113
	v_rcp_f32_e32 v114, v114
	v_rcp_f32_e32 v115, v115
	v_exp_f32_e64 v109, -v101
	v_exp_f32_e64 v110, -v102
	v_exp_f32_e64 v111, -v103
	v_pk_mul_f32 v[104:105], v[112:113], v[104:105]
	v_pk_mul_f32 v[106:107], v[114:115], v[106:107]
	v_cvt_pk_bf16_f32 v104, v104, v105
	v_pk_mul_f32 v[98:99], v[102:103], v[98:99]
	v_cvt_pk_bf16_f32 v105, v106, v107
; template <int N, int K, int EPI>
; __device__ void gemm_phase(const u16* __restrict__ A, const u16* __restrict__ Bt, const EpiArgs ea, char* smem, int tid) {
;     ...
;         for (int ai = 0; ai < 2; ++ai)
; #pragma unroll
;           for (int m = 0; m < 4; ++m) {
;             const int row = brow + ai * HALF + wr * 64 + m * 16 + fr_e;
;             const int col = pn * 128 + wc * 32 + fq_e * 8;
;             u32x4 o;
; #pragma unroll
;             for (int n = 0; n < 2; ++n) {
;               const f32x4 t4 = acc[ai][0][m][n], u4 = acc[ai][1][m][n];
;               f32x2 tl = {t4[0], t4[1]}, th = {t4[2], t4[3]}, ul = {u4[0], u4[1]}, uh = {u4[2], u4[3]};
;               f32x2 el = {__builtin_amdgcn_exp2f(-t4[0]), __builtin_amdgcn_exp2f(-t4[1])};
;               f32x2 eh = {__builtin_amdgcn_exp2f(-t4[2]), __builtin_amdgcn_exp2f(-t4[3])};
;               el = el + 1.f; eh = eh + 1.f;
;               f32x2 rl = {__builtin_amdgcn_rcpf(el[0]), __builtin_amdgcn_rcpf(el[1])};
;               f32x2 rh = {__builtin_amdgcn_rcpf(eh[0]), __builtin_amdgcn_rcpf(eh[1])};
;               const f32x2 hl = tl * ul * rl, hh2 = th * uh * rh;
;               o[2 * n] = pk_bf16(hl[0], hl[1]); o[2 * n + 1] = pk_bf16(hh2[0], hh2[1]);
;             }
;             *(u32x4*)(h + (size_t)row * FF + col) = o;
	v_pk_add_f32 v[106:107], v[108:109], 1.0 op_sel_hi:[1,0]
	v_pk_add_f32 v[108:109], v[110:111], 1.0 op_sel_hi:[1,0]
	v_rcp_f32_e32 v106, v106
	v_rcp_f32_e32 v107, v107
	v_rcp_f32_e32 v108, v108
	v_rcp_f32_e32 v109, v109
	v_pk_mul_f32 v[96:97], v[100:101], v[96:97]
	v_pk_mul_f32 v[90:91], v[94:95], v[90:91]
	v_pk_mul_f32 v[96:97], v[106:107], v[96:97]
	v_pk_mul_f32 v[98:99], v[108:109], v[98:99]
	v_cvt_pk_bf16_f32 v106, v96, v97
	v_exp_f32_e64 v96, -v92
	v_cvt_pk_bf16_f32 v107, v98, v99
	v_exp_f32_e64 v97, -v93
	v_exp_f32_e64 v98, -v94
	v_exp_f32_e64 v99, -v95
	v_pk_mul_f32 v[88:89], v[92:93], v[88:89]
	v_pk_add_f32 v[96:97], v[96:97], 1.0 op_sel_hi:[1,0]
	v_exp_f32_e64 v92, -v84
	v_pk_add_f32 v[98:99], v[98:99], 1.0 op_sel_hi:[1,0]
	v_rcp_f32_e32 v96, v96
	v_rcp_f32_e32 v97, v97
	v_rcp_f32_e32 v98, v98
	v_rcp_f32_e32 v99, v99
	v_exp_f32_e64 v93, -v85
	v_exp_f32_e64 v94, -v86
	v_exp_f32_e64 v95, -v87
	v_pk_mul_f32 v[88:89], v[96:97], v[88:89]
	v_pk_mul_f32 v[90:91], v[98:99], v[90:91]
	v_cvt_pk_bf16_f32 v88, v88, v89
	v_pk_mul_f32 v[82:83], v[86:87], v[82:83]
	v_cvt_pk_bf16_f32 v89, v90, v91
	v_pk_add_f32 v[90:91], v[92:93], 1.0 op_sel_hi:[1,0]
	v_pk_add_f32 v[92:93], v[94:95], 1.0 op_sel_hi:[1,0]
	v_rcp_f32_e32 v90, v90
	v_rcp_f32_e32 v91, v91
	v_rcp_f32_e32 v92, v92
	v_rcp_f32_e32 v93, v93
	v_pk_mul_f32 v[80:81], v[84:85], v[80:81]
	v_pk_mul_f32 v[74:75], v[78:79], v[74:75]
	v_pk_mul_f32 v[80:81], v[90:91], v[80:81]
	v_pk_mul_f32 v[82:83], v[92:93], v[82:83]
	v_cvt_pk_bf16_f32 v90, v80, v81
	v_exp_f32_e64 v80, -v76
	v_cvt_pk_bf16_f32 v91, v82, v83
	v_exp_f32_e64 v81, -v77
	v_exp_f32_e64 v82, -v78
	v_exp_f32_e64 v83, -v79
	v_pk_mul_f32 v[72:73], v[76:77], v[72:73]
	v_pk_add_f32 v[80:81], v[80:81], 1.0 op_sel_hi:[1,0]
	v_exp_f32_e64 v76, -v68
	v_pk_add_f32 v[82:83], v[82:83], 1.0 op_sel_hi:[1,0]
	v_rcp_f32_e32 v80, v80
	v_rcp_f32_e32 v81, v81
	v_rcp_f32_e32 v82, v82
	v_rcp_f32_e32 v83, v83
	v_exp_f32_e64 v77, -v69
	v_exp_f32_e64 v78, -v70
	v_exp_f32_e64 v79, -v71
	v_pk_mul_f32 v[72:73], v[80:81], v[72:73]
	v_pk_mul_f32 v[74:75], v[82:83], v[74:75]
	v_cvt_pk_bf16_f32 v72, v72, v73
	s_lshl_b32 s3, s77, 8
	v_cvt_pk_bf16_f32 v73, v74, v75
	v_pk_add_f32 v[74:75], v[76:77], 1.0 op_sel_hi:[1,0]
	v_pk_add_f32 v[76:77], v[78:79], 1.0 op_sel_hi:[1,0]
	v_rcp_f32_e32 v74, v74
	v_rcp_f32_e32 v76, v76
	v_rcp_f32_e32 v77, v77
	v_rcp_f32_e32 v75, v75
	v_mov_b32_e32 v128, v132
	v_mov_b32_e32 v129, v131
	s_add_i32 s3, s3, s43
	v_pk_mul_f32 v[66:67], v[70:71], v[66:67]
	v_add_u32_e32 v142, s3, v129
	s_lshl_b32 s3, s73, 7
	s_or_b32 s3, s3, s66
	v_pk_mul_f32 v[64:65], v[68:69], v[64:65]
	v_pk_mul_f32 v[66:67], v[76:77], v[66:67]
	v_lshl_add_u32 v128, v128, 3, s3
	v_pk_mul_f32 v[64:65], v[74:75], v[64:65]
	v_cvt_pk_bf16_f32 v75, v66, v67
	v_exp_f32_e64 v66, -v60
	v_exp_f32_e64 v67, -v61
	v_exp_f32_e64 v68, -v62
	v_exp_f32_e64 v69, -v63
	v_ashrrev_i32_e32 v129, 31, v128
	v_lshl_add_u64 v[128:129], v[128:129], 1, s[80:81]
	v_cvt_pk_bf16_f32 v74, v64, v65
	v_add_u32_e32 v64, 48, v142
	v_mad_i64_i32 v[64:65], s[10:11], v64, s68, v[128:129]
	global_store_dwordx4 v[64:65], v[72:75], off
	v_pk_add_f32 v[64:65], v[66:67], 1.0 op_sel_hi:[1,0]
	v_pk_add_f32 v[66:67], v[68:69], 1.0 op_sel_hi:[1,0]
	v_rcp_f32_e32 v64, v64
	v_rcp_f32_e32 v65, v65
	v_rcp_f32_e32 v66, v66
	v_rcp_f32_e32 v67, v67
	v_pk_mul_f32 v[58:59], v[62:63], v[58:59]
	v_pk_mul_f32 v[56:57], v[60:61], v[56:57]
	v_exp_f32_e64 v60, -v52
	v_exp_f32_e64 v61, -v53
	v_exp_f32_e64 v62, -v54
	v_exp_f32_e64 v63, -v55
	v_pk_mul_f32 v[56:57], v[64:65], v[56:57]
	v_pk_mul_f32 v[58:59], v[66:67], v[58:59]
	v_cvt_pk_bf16_f32 v56, v56, v57
	v_pk_mul_f32 v[50:51], v[54:55], v[50:51]
	v_cvt_pk_bf16_f32 v57, v58, v59
	v_pk_add_f32 v[58:59], v[60:61], 1.0 op_sel_hi:[1,0]
	v_pk_add_f32 v[60:61], v[62:63], 1.0 op_sel_hi:[1,0]
	v_rcp_f32_e32 v58, v58
	v_rcp_f32_e32 v59, v59
	v_rcp_f32_e32 v60, v60
	v_rcp_f32_e32 v61, v61
	v_pk_mul_f32 v[48:49], v[52:53], v[48:49]
	v_pk_mul_f32 v[42:43], v[46:47], v[42:43]
	v_pk_mul_f32 v[48:49], v[58:59], v[48:49]
	v_pk_mul_f32 v[50:51], v[60:61], v[50:51]
	v_cvt_pk_bf16_f32 v58, v48, v49
	v_exp_f32_e64 v48, -v44
	v_cvt_pk_bf16_f32 v59, v50, v51
	v_exp_f32_e64 v49, -v45
	v_exp_f32_e64 v50, -v46
	v_exp_f32_e64 v51, -v47
	v_pk_mul_f32 v[40:41], v[44:45], v[40:41]
; template <int N, int K, int EPI>
; __device__ void gemm_phase(const u16* __restrict__ A, const u16* __restrict__ Bt, const EpiArgs ea, char* smem, int tid) {
;     ...
;         for (int ai = 0; ai < 2; ++ai)
; #pragma unroll
;           for (int m = 0; m < 4; ++m) {
;             const int row = brow + ai * HALF + wr * 64 + m * 16 + fr_e;
;             const int col = pn * 128 + wc * 32 + fq_e * 8;
;             u32x4 o;
; #pragma unroll
;             for (int n = 0; n < 2; ++n) {
;               const f32x4 t4 = acc[ai][0][m][n], u4 = acc[ai][1][m][n];
;               f32x2 tl = {t4[0], t4[1]}, th = {t4[2], t4[3]}, ul = {u4[0], u4[1]}, uh = {u4[2], u4[3]};
;               f32x2 el = {__builtin_amdgcn_exp2f(-t4[0]), __builtin_amdgcn_exp2f(-t4[1])};
;               f32x2 eh = {__builtin_amdgcn_exp2f(-t4[2]), __builtin_amdgcn_exp2f(-t4[3])};
;               el = el + 1.f; eh = eh + 1.f;
;               f32x2 rl = {__builtin_amdgcn_rcpf(el[0]), __builtin_amdgcn_rcpf(el[1])};
;               f32x2 rh = {__builtin_amdgcn_rcpf(eh[0]), __builtin_amdgcn_rcpf(eh[1])};
;               const f32x2 hl = tl * ul * rl, hh2 = th * uh * rh;
;               o[2 * n] = pk_bf16(hl[0], hl[1]); o[2 * n + 1] = pk_bf16(hh2[0], hh2[1]);
;             }
;             *(u32x4*)(h + (size_t)row * FF + col) = o;
;           }
;     ...
;     if (!has_next) break;
	v_pk_add_f32 v[48:49], v[48:49], 1.0 op_sel_hi:[1,0]
	v_exp_f32_e64 v44, -v36
	v_pk_add_f32 v[50:51], v[50:51], 1.0 op_sel_hi:[1,0]
	v_rcp_f32_e32 v48, v48
	v_rcp_f32_e32 v49, v49
	v_rcp_f32_e32 v50, v50
	v_rcp_f32_e32 v51, v51
	v_exp_f32_e64 v45, -v37
	v_exp_f32_e64 v46, -v38
	v_exp_f32_e64 v47, -v39
	v_pk_mul_f32 v[40:41], v[48:49], v[40:41]
	v_pk_mul_f32 v[42:43], v[50:51], v[42:43]
	v_cvt_pk_bf16_f32 v40, v40, v41
	v_pk_mul_f32 v[34:35], v[38:39], v[34:35]
	v_cvt_pk_bf16_f32 v41, v42, v43
	v_pk_add_f32 v[42:43], v[44:45], 1.0 op_sel_hi:[1,0]
	v_pk_add_f32 v[44:45], v[46:47], 1.0 op_sel_hi:[1,0]
	v_rcp_f32_e32 v42, v42
	v_rcp_f32_e32 v43, v43
	v_rcp_f32_e32 v44, v44
	v_rcp_f32_e32 v45, v45
	v_pk_mul_f32 v[32:33], v[36:37], v[32:33]
	v_pk_mul_f32 v[26:27], v[30:31], v[26:27]
	v_pk_mul_f32 v[32:33], v[42:43], v[32:33]
	v_pk_mul_f32 v[34:35], v[44:45], v[34:35]
	v_cvt_pk_bf16_f32 v42, v32, v33
	v_exp_f32_e64 v32, -v28
	v_cvt_pk_bf16_f32 v43, v34, v35
	v_exp_f32_e64 v33, -v29
	v_exp_f32_e64 v34, -v30
	v_exp_f32_e64 v35, -v31
	v_pk_mul_f32 v[24:25], v[28:29], v[24:25]
	v_pk_add_f32 v[32:33], v[32:33], 1.0 op_sel_hi:[1,0]
	v_exp_f32_e64 v28, -v20
	v_pk_add_f32 v[34:35], v[34:35], 1.0 op_sel_hi:[1,0]
	v_rcp_f32_e32 v32, v32
	v_rcp_f32_e32 v33, v33
	v_rcp_f32_e32 v34, v34
	v_rcp_f32_e32 v35, v35
	v_exp_f32_e64 v29, -v21
	v_exp_f32_e64 v30, -v22
	v_exp_f32_e64 v31, -v23
	v_pk_mul_f32 v[24:25], v[32:33], v[24:25]
	v_pk_mul_f32 v[26:27], v[34:35], v[26:27]
	v_cvt_pk_bf16_f32 v24, v24, v25
	v_pk_mul_f32 v[18:19], v[22:23], v[18:19]
	v_cvt_pk_bf16_f32 v25, v26, v27
	v_pk_add_f32 v[26:27], v[28:29], 1.0 op_sel_hi:[1,0]
	v_pk_add_f32 v[28:29], v[30:31], 1.0 op_sel_hi:[1,0]
	v_rcp_f32_e32 v26, v26
	v_rcp_f32_e32 v27, v27
	v_rcp_f32_e32 v28, v28
	v_rcp_f32_e32 v29, v29
	v_pk_mul_f32 v[16:17], v[20:21], v[16:17]
	v_pk_mul_f32 v[8:9], v[12:13], v[8:9]
	v_pk_mul_f32 v[16:17], v[26:27], v[16:17]
	v_pk_mul_f32 v[18:19], v[28:29], v[18:19]
	v_cvt_pk_bf16_f32 v26, v16, v17
	v_exp_f32_e64 v16, -v12
	v_cvt_pk_bf16_f32 v27, v18, v19
	v_exp_f32_e64 v17, -v13
	v_exp_f32_e64 v18, -v14
	v_exp_f32_e64 v19, -v15
	v_exp_f32_e64 v12, -v4
	v_pk_add_f32 v[16:17], v[16:17], 1.0 op_sel_hi:[1,0]
	v_exp_f32_e64 v13, -v5
	v_pk_add_f32 v[18:19], v[18:19], 1.0 op_sel_hi:[1,0]
	v_rcp_f32_e32 v16, v16
	v_rcp_f32_e32 v17, v17
	v_rcp_f32_e32 v18, v18
	v_rcp_f32_e32 v19, v19
	v_pk_mul_f32 v[10:11], v[14:15], v[10:11]
	v_pk_mul_f32 v[8:9], v[16:17], v[8:9]
	v_exp_f32_e64 v14, -v6
	v_pk_mul_f32 v[10:11], v[18:19], v[10:11]
	v_exp_f32_e64 v15, -v7
	v_cvt_pk_bf16_f32 v8, v8, v9
	v_cvt_pk_bf16_f32 v9, v10, v11
	v_pk_add_f32 v[10:11], v[12:13], 1.0 op_sel_hi:[1,0]
	v_pk_add_f32 v[12:13], v[14:15], 1.0 op_sel_hi:[1,0]
	v_rcp_f32_e32 v10, v10
	v_rcp_f32_e32 v11, v11
	v_pk_mul_f32 v[0:1], v[4:5], v[0:1]
	v_rcp_f32_e32 v12, v12
	v_rcp_f32_e32 v13, v13
	v_pk_mul_f32 v[0:1], v[10:11], v[0:1]
	v_add_u32_e32 v100, 16, v142
	v_add_u32_e32 v84, 32, v142
	v_add_u32_e32 v70, 0x80, v142
	v_add_u32_e32 v36, 0x90, v142
	v_add_u32_e32 v20, 0xa0, v142
	v_cvt_pk_bf16_f32 v10, v0, v1
	v_add_u32_e32 v0, 0xb0, v142
	v_mad_i64_i32 v[116:117], s[10:11], v142, s68, v[128:129]
	v_mad_i64_i32 v[100:101], s[10:11], v100, s68, v[128:129]
	v_mad_i64_i32 v[84:85], s[10:11], v84, s68, v[128:129]
	v_mad_i64_i32 v[52:53], s[10:11], v70, s68, v[128:129]
	v_mad_i64_i32 v[36:37], s[10:11], v36, s68, v[128:129]
	v_mad_i64_i32 v[20:21], s[10:11], v20, s68, v[128:129]
	v_mad_i64_i32 v[0:1], s[10:11], v0, s68, v[128:129]
	v_pk_mul_f32 v[2:3], v[6:7], v[2:3]
	s_and_b64 vcc, exec, s[0:1]
	s_mov_b32 s77, s2
	s_mov_b32 s73, s4
	s_mov_b64 s[12:13], s[8:9]
	s_mov_b64 s[10:11], s[6:7]
	global_store_dwordx4 v[116:117], v[120:123], off
	global_store_dwordx4 v[100:101], v[104:107], off
	global_store_dwordx4 v[84:85], v[88:91], off
	global_store_dwordx4 v[52:53], v[56:59], off
	global_store_dwordx4 v[36:37], v[40:43], off
	global_store_dwordx4 v[20:21], v[24:27], off
	v_pk_mul_f32 v[2:3], v[12:13], v[2:3]
	s_nop 0
	v_cvt_pk_bf16_f32 v11, v2, v3
	global_store_dwordx4 v[0:1], v[8:11], off
	s_cbranch_vccz .LBB0_233
	s_waitcnt vmcnt(0)
	v_readlane_b32 s36, v226, 30
	s_cmpk_gt_u32 s22, 0xff
	s_mov_b64 s[34:35], s[96:97]
	v_readlane_b32 s37, v226, 31
	s_cbranch_scc1 .LBB0_240
	s_barrier
